# priority flips kept but moved off the hand-off chain (setprio 1 before opening barrier, setprio 0 after closing barrier)
# speedup vs baseline: 1.0096x; 1.0096x over previous
; #define PG8_STAGE(bufoff, gbase, voff) do { _Pragma("unroll") for (int _i = 0; _i < 2; ++_i) \
;         __builtin_amdgcn_global_load_lds((const unsigned*)((const char*)(gbase) + (voff)[_i]), (LAS unsigned*)(lds + (bufoff) + ldsw + _i * 8192), 16, 0, 0); } while (0)
; #define PG8_LDA(dst, b, h) do { _Pragma("unroll") for (int m = 0; m < 4; ++m) _Pragma("unroll") for (int k = 0; k < 2; ++k) dst[m][k] = *(const LAS bf16x8*)(lds + PG8_SA(b, h) + aoff + m * 2048 + k * 1024); } while (0)
; #define PG8_LDB(dst, b, h) do { _Pragma("unroll") for (int n = 0; n < 2; ++n) _Pragma("unroll") for (int k = 0; k < 2; ++k) dst[n][k] = *(const LAS bf16x8*)(lds + PG8_SB(b, h) + boff + n * 2048 + k * 1024); } while (0)
; #define PG8_MMA(ai, bj, At, Bt) do { __builtin_amdgcn_s_setprio(1); _Pragma("unroll") for (int m = 0; m < 4; ++m) _Pragma("unroll") for (int n = 0; n < 2; ++n) _Pragma("unroll") for (int k = 0; k < 2; ++k) \
;         acc[ai][bj][m][n] = __builtin_amdgcn_mfma_f32_16x16x32_bf16(Bt[n][k], At[m][k], acc[ai][bj][m][n], 0, 0, 0); __builtin_amdgcn_s_setprio(0); } while (0)
; #define PG8_WAIT_V(n) asm volatile("s_waitcnt vmcnt(" #n ")" ::: "memory")
; #define PG8_WAIT_L(n) asm volatile("s_waitcnt lgkmcnt(" #n ")" ::: "memory")
; #define PG8_BAR __builtin_amdgcn_s_barrier()
; #define PG8_SCHED __builtin_amdgcn_sched_barrier(0)
; template <class Epi, bool ALIGN_EPI, bool SP2 = PG8_SP2_DEFAULT>
; __device__ __forceinline__ void gemm_phase(LAS unsigned char* lds, const Gemm g, const StaticOrder& S, const Epi& E) {
;     ...
;             PG8_LDB(B0, 0, 0); PG8_LDB(B1, 0, 1); PG8_SCHED; PG8_LDA(At, 0, 0); PG8_STAGE(PG8_SA(1, 1), a1 + hstepA, voffA);
;             PG8_WAIT_V(8); PG8_WAIT_L(0); PG8_BAR; PG8_MMA(0, 0, At, B0); PG8_MMA(0, 1, At, B1); PG8_BAR; PG8_SCHED;
;             PG8_LDA(At, 0, 1); PG8_STAGE(PG8_SB(0, 0), b2, voffB); PG8_STAGE(PG8_SB(0, 1), b2 + hstepB, voffB); PG8_STAGE(PG8_SA(0, 0), a2, voffA);
.LBB0_250:
	ds_read_b128 v[150:153], v147
	ds_read_b128 v[154:157], v147 offset:1024
	ds_read_b128 v[158:161], v147 offset:2048
	ds_read_b128 v[162:165], v147 offset:3072
	ds_read_b128 v[166:169], v148
	ds_read_b128 v[170:173], v148 offset:1024
	ds_read_b128 v[174:177], v148 offset:2048
	ds_read_b128 v[178:181], v148 offset:3072
	s_add_u32 s20, s18, 0xfff00080
	s_addc_u32 s21, s19, -1
	s_cmp_eq_u32 s44, 60
	s_cselect_b32 s23, s13, s21
	s_cselect_b32 s22, s40, s20
	s_cselect_b32 s21, s11, s43
	s_cselect_b32 s20, s41, s42
	v_lshl_add_u64 v[206:207], s[18:19], 0, v[136:137]
	s_add_i32 m0, s9, 0xc000
	ds_read_b128 v[182:185], v149
	ds_read_b128 v[186:189], v149 offset:1024
	ds_read_b128 v[190:193], v149 offset:2048
	ds_read_b128 v[198:201], v149 offset:3072
	ds_read_b128 v[202:205], v149 offset:4096
	ds_read_b128 v[216:219], v149 offset:5120
	ds_read_b128 v[220:223], v149 offset:6144
	ds_read_b128 v[224:227], v149 offset:7168
	global_load_lds_dwordx4 v[206:207], off
	v_lshl_add_u64 v[206:207], s[18:19], 0, v[138:139]
	s_add_i32 m0, s9, 0xe000
	s_nop 0
	global_load_lds_dwordx4 v[206:207], off
	s_waitcnt vmcnt(8)
	s_waitcnt lgkmcnt(0)
	s_setprio 1
	s_barrier
	v_mfma_f32_16x16x32_bf16 v[124:127], v[150:153], v[182:185], v[124:127]
	v_mfma_f32_16x16x32_bf16 v[120:123], v[158:161], v[182:185], v[120:123]
	v_mfma_f32_16x16x32_bf16 v[116:119], v[150:153], v[190:193], v[116:119]
	v_mfma_f32_16x16x32_bf16 v[112:115], v[158:161], v[190:193], v[112:115]
	v_mfma_f32_16x16x32_bf16 v[100:103], v[150:153], v[202:205], v[100:103]
	v_mfma_f32_16x16x32_bf16 v[96:99], v[158:161], v[202:205], v[96:99]
	v_mfma_f32_16x16x32_bf16 v[84:87], v[150:153], v[220:223], v[84:87]
	v_mfma_f32_16x16x32_bf16 v[80:83], v[158:161], v[220:223], v[80:83]
	v_mfma_f32_16x16x32_bf16 v[124:127], v[154:157], v[186:189], v[124:127]
	v_mfma_f32_16x16x32_bf16 v[120:123], v[162:165], v[186:189], v[120:123]
	v_mfma_f32_16x16x32_bf16 v[116:119], v[154:157], v[198:201], v[116:119]
	v_mfma_f32_16x16x32_bf16 v[112:115], v[162:165], v[198:201], v[112:115]
	v_mfma_f32_16x16x32_bf16 v[100:103], v[154:157], v[216:219], v[100:103]
	v_mfma_f32_16x16x32_bf16 v[96:99], v[162:165], v[216:219], v[96:99]
	v_mfma_f32_16x16x32_bf16 v[84:87], v[154:157], v[224:227], v[84:87]
	v_mfma_f32_16x16x32_bf16 v[80:83], v[162:165], v[224:227], v[80:83]
	v_mfma_f32_16x16x32_bf16 v[108:111], v[166:169], v[182:185], v[108:111]
	v_mfma_f32_16x16x32_bf16 v[104:107], v[174:177], v[182:185], v[104:107]
	v_mfma_f32_16x16x32_bf16 v[92:95], v[166:169], v[190:193], v[92:95]
	v_mfma_f32_16x16x32_bf16 v[88:91], v[174:177], v[190:193], v[88:91]
	v_mfma_f32_16x16x32_bf16 v[76:79], v[166:169], v[202:205], v[76:79]
	v_mfma_f32_16x16x32_bf16 v[72:75], v[174:177], v[202:205], v[72:75]
	v_mfma_f32_16x16x32_bf16 v[68:71], v[166:169], v[220:223], v[68:71]
	v_mfma_f32_16x16x32_bf16 v[64:67], v[174:177], v[220:223], v[64:67]
	v_mfma_f32_16x16x32_bf16 v[108:111], v[170:173], v[186:189], v[108:111]
	v_mfma_f32_16x16x32_bf16 v[104:107], v[178:181], v[186:189], v[104:107]
	v_mfma_f32_16x16x32_bf16 v[92:95], v[170:173], v[198:201], v[92:95]
	v_mfma_f32_16x16x32_bf16 v[88:91], v[178:181], v[198:201], v[88:91]
	v_mfma_f32_16x16x32_bf16 v[76:79], v[170:173], v[216:219], v[76:79]
	v_mfma_f32_16x16x32_bf16 v[72:75], v[178:181], v[216:219], v[72:75]
	v_mfma_f32_16x16x32_bf16 v[68:71], v[170:173], v[224:227], v[68:71]
	v_mfma_f32_16x16x32_bf16 v[64:67], v[178:181], v[224:227], v[64:67]
	s_barrier
	s_setprio 0
	s_add_i32 s45, s36, s24
	v_lshl_add_u64 v[206:207], s[20:21], 0, v[132:133]
	s_mov_b32 m0, s45
	ds_read_b128 v[182:185], v149 offset:16384
	ds_read_b128 v[186:189], v149 offset:17408
	ds_read_b128 v[190:193], v149 offset:18432
	ds_read_b128 v[198:201], v149 offset:19456
	ds_read_b128 v[202:205], v149 offset:20480
	ds_read_b128 v[216:219], v149 offset:21504
	ds_read_b128 v[220:223], v149 offset:22528
	ds_read_b128 v[224:227], v149 offset:23552
	global_load_lds_dwordx4 v[206:207], off
	s_add_i32 m0, s45, 0x2000
	s_add_u32 s46, s20, 0x100000
	v_lshl_add_u64 v[210:211], s[20:21], 0, v[128:129]
	s_addc_u32 s47, s21, 0
	s_add_i32 s45, s37, s24
	global_load_lds_dwordx4 v[210:211], off
	v_lshl_add_u64 v[228:229], s[46:47], 0, v[132:133]
	s_mov_b32 m0, s45
	v_lshl_add_u64 v[230:231], s[22:23], 0, v[130:131]
	global_load_lds_dwordx4 v[228:229], off
	v_lshl_add_u64 v[228:229], s[46:47], 0, v[128:129]
	s_add_i32 m0, s45, 0x2000
	s_nop 0
	global_load_lds_dwordx4 v[228:229], off
	v_lshl_add_u64 v[228:229], s[22:23], 0, v[134:135]
	s_mov_b32 m0, s9
	s_nop 0
	global_load_lds_dwordx4 v[228:229], off
	s_mov_b32 m0, s27
	s_nop 0
	global_load_lds_dwordx4 v[230:231], off
	s_waitcnt vmcnt(8)
	s_waitcnt lgkmcnt(0)
	s_setprio 1
	s_barrier
; #define PG8_STAGE(bufoff, gbase, voff) do { _Pragma("unroll") for (int _i = 0; _i < 2; ++_i) \
;         __builtin_amdgcn_global_load_lds((const unsigned*)((const char*)(gbase) + (voff)[_i]), (LAS unsigned*)(lds + (bufoff) + ldsw + _i * 8192), 16, 0, 0); } while (0)
; #define PG8_LDA(dst, b, h) do { _Pragma("unroll") for (int m = 0; m < 4; ++m) _Pragma("unroll") for (int k = 0; k < 2; ++k) dst[m][k] = *(const LAS bf16x8*)(lds + PG8_SA(b, h) + aoff + m * 2048 + k * 1024); } while (0)
; #define PG8_LDB(dst, b, h) do { _Pragma("unroll") for (int n = 0; n < 2; ++n) _Pragma("unroll") for (int k = 0; k < 2; ++k) dst[n][k] = *(const LAS bf16x8*)(lds + PG8_SB(b, h) + boff + n * 2048 + k * 1024); } while (0)
; #define PG8_MMA(ai, bj, At, Bt) do { __builtin_amdgcn_s_setprio(1); _Pragma("unroll") for (int m = 0; m < 4; ++m) _Pragma("unroll") for (int n = 0; n < 2; ++n) _Pragma("unroll") for (int k = 0; k < 2; ++k) \
;         acc[ai][bj][m][n] = __builtin_amdgcn_mfma_f32_16x16x32_bf16(Bt[n][k], At[m][k], acc[ai][bj][m][n], 0, 0, 0); __builtin_amdgcn_s_setprio(0); } while (0)
; #define PG8_WAIT_V(n) asm volatile("s_waitcnt vmcnt(" #n ")" ::: "memory")
; #define PG8_WAIT_L(n) asm volatile("s_waitcnt lgkmcnt(" #n ")" ::: "memory")
; #define PG8_BAR __builtin_amdgcn_s_barrier()
; #define PG8_SCHED __builtin_amdgcn_sched_barrier(0)
; template <class Epi, bool ALIGN_EPI, bool SP2 = PG8_SP2_DEFAULT>
; __device__ __forceinline__ void gemm_phase(LAS unsigned char* lds, const Gemm g, const StaticOrder& S, const Epi& E) {
;     ...
;             PG8_WAIT_V(8); PG8_WAIT_L(0); PG8_BAR; PG8_MMA(1, 0, At, B0); PG8_MMA(1, 1, At, B1); PG8_BAR; PG8_SCHED;
;             PG8_LDB(B0, 1, 0); PG8_LDB(B1, 1, 1); PG8_SCHED; PG8_LDA(At, 1, 0); PG8_STAGE(PG8_SA(0, 1), a2 + hstepA, voffA);
;             PG8_WAIT_V(8); PG8_WAIT_L(0); PG8_BAR; PG8_MMA(0, 0, At, B0); PG8_MMA(0, 1, At, B1); PG8_BAR; PG8_SCHED;
	v_mfma_f32_16x16x32_bf16 v[60:63], v[150:153], v[182:185], v[60:63]
	v_mfma_f32_16x16x32_bf16 v[56:59], v[158:161], v[182:185], v[56:59]
	v_mfma_f32_16x16x32_bf16 v[52:55], v[150:153], v[190:193], v[52:55]
	v_mfma_f32_16x16x32_bf16 v[48:51], v[158:161], v[190:193], v[48:51]
	v_mfma_f32_16x16x32_bf16 v[36:39], v[150:153], v[202:205], v[36:39]
	v_mfma_f32_16x16x32_bf16 v[32:35], v[158:161], v[202:205], v[32:35]
	v_mfma_f32_16x16x32_bf16 v[20:23], v[150:153], v[220:223], v[20:23]
	v_mfma_f32_16x16x32_bf16 v[16:19], v[158:161], v[220:223], v[16:19]
	v_mfma_f32_16x16x32_bf16 v[60:63], v[154:157], v[186:189], v[60:63]
	v_mfma_f32_16x16x32_bf16 v[56:59], v[162:165], v[186:189], v[56:59]
	v_mfma_f32_16x16x32_bf16 v[52:55], v[154:157], v[198:201], v[52:55]
	v_mfma_f32_16x16x32_bf16 v[48:51], v[162:165], v[198:201], v[48:51]
	v_mfma_f32_16x16x32_bf16 v[36:39], v[154:157], v[216:219], v[36:39]
	v_mfma_f32_16x16x32_bf16 v[32:35], v[162:165], v[216:219], v[32:35]
	v_mfma_f32_16x16x32_bf16 v[20:23], v[154:157], v[224:227], v[20:23]
	v_mfma_f32_16x16x32_bf16 v[16:19], v[162:165], v[224:227], v[16:19]
	v_mfma_f32_16x16x32_bf16 v[44:47], v[166:169], v[182:185], v[44:47]
	v_mfma_f32_16x16x32_bf16 v[40:43], v[174:177], v[182:185], v[40:43]
	v_mfma_f32_16x16x32_bf16 v[28:31], v[166:169], v[190:193], v[28:31]
	v_mfma_f32_16x16x32_bf16 v[24:27], v[174:177], v[190:193], v[24:27]
	v_mfma_f32_16x16x32_bf16 v[12:15], v[166:169], v[202:205], v[12:15]
	v_mfma_f32_16x16x32_bf16 v[8:11], v[174:177], v[202:205], v[8:11]
	v_mfma_f32_16x16x32_bf16 v[4:7], v[166:169], v[220:223], v[4:7]
	v_mfma_f32_16x16x32_bf16 v[0:3], v[174:177], v[220:223], v[0:3]
	v_mfma_f32_16x16x32_bf16 v[44:47], v[170:173], v[186:189], v[44:47]
	v_mfma_f32_16x16x32_bf16 v[40:43], v[178:181], v[186:189], v[40:43]
	v_mfma_f32_16x16x32_bf16 v[28:31], v[170:173], v[198:201], v[28:31]
	v_mfma_f32_16x16x32_bf16 v[24:27], v[178:181], v[198:201], v[24:27]
	v_mfma_f32_16x16x32_bf16 v[12:15], v[170:173], v[216:219], v[12:15]
	v_mfma_f32_16x16x32_bf16 v[8:11], v[178:181], v[216:219], v[8:11]
	v_mfma_f32_16x16x32_bf16 v[4:7], v[170:173], v[224:227], v[4:7]
	v_mfma_f32_16x16x32_bf16 v[0:3], v[178:181], v[224:227], v[0:3]
	s_barrier
	s_setprio 0
	s_add_i32 s45, 0, 0x18000
	s_add_i32 s46, 0, 0x1c000
	v_add_u32_e32 v162, s45, v145
	v_add_u32_e32 v178, s46, v145
	ds_read_b128 v[150:153], v162
	ds_read_b128 v[154:157], v162 offset:1024
	ds_read_b128 v[158:161], v162 offset:2048
	ds_read_b128 v[162:165], v162 offset:3072
	ds_read_b128 v[166:169], v178
	ds_read_b128 v[170:173], v178 offset:1024
	ds_read_b128 v[174:177], v178 offset:2048
	ds_read_b128 v[178:181], v178 offset:3072
	s_add_u32 s22, s22, 0x100000
	s_addc_u32 s23, s23, 0
	s_mov_b32 m0, s28
	v_lshl_add_u64 v[232:233], s[22:23], 0, v[134:135]
	ds_read_b128 v[182:185], v149 offset:32768
	ds_read_b128 v[186:189], v149 offset:33792
	ds_read_b128 v[190:193], v149 offset:34816
	ds_read_b128 v[198:201], v149 offset:35840
	ds_read_b128 v[202:205], v149 offset:36864
	ds_read_b128 v[216:219], v149 offset:37888
	ds_read_b128 v[220:223], v149 offset:38912
	ds_read_b128 v[224:227], v149 offset:39936
	global_load_lds_dwordx4 v[232:233], off
	v_lshl_add_u64 v[232:233], s[22:23], 0, v[130:131]
	s_mov_b32 m0, s29
	s_nop 0
	global_load_lds_dwordx4 v[232:233], off
	s_waitcnt vmcnt(8)
	s_waitcnt lgkmcnt(0)
	s_setprio 1
	s_barrier
	v_mfma_f32_16x16x32_bf16 v[124:127], v[150:153], v[182:185], v[124:127]
	v_mfma_f32_16x16x32_bf16 v[120:123], v[158:161], v[182:185], v[120:123]
	v_mfma_f32_16x16x32_bf16 v[116:119], v[150:153], v[190:193], v[116:119]
	v_mfma_f32_16x16x32_bf16 v[112:115], v[158:161], v[190:193], v[112:115]
	v_mfma_f32_16x16x32_bf16 v[100:103], v[150:153], v[202:205], v[100:103]
	v_mfma_f32_16x16x32_bf16 v[96:99], v[158:161], v[202:205], v[96:99]
	v_mfma_f32_16x16x32_bf16 v[84:87], v[150:153], v[220:223], v[84:87]
	v_mfma_f32_16x16x32_bf16 v[80:83], v[158:161], v[220:223], v[80:83]
	v_mfma_f32_16x16x32_bf16 v[124:127], v[154:157], v[186:189], v[124:127]
	v_mfma_f32_16x16x32_bf16 v[120:123], v[162:165], v[186:189], v[120:123]
	v_mfma_f32_16x16x32_bf16 v[116:119], v[154:157], v[198:201], v[116:119]
	v_mfma_f32_16x16x32_bf16 v[112:115], v[162:165], v[198:201], v[112:115]
	v_mfma_f32_16x16x32_bf16 v[100:103], v[154:157], v[216:219], v[100:103]
	v_mfma_f32_16x16x32_bf16 v[96:99], v[162:165], v[216:219], v[96:99]
	v_mfma_f32_16x16x32_bf16 v[84:87], v[154:157], v[224:227], v[84:87]
	v_mfma_f32_16x16x32_bf16 v[80:83], v[162:165], v[224:227], v[80:83]
	v_mfma_f32_16x16x32_bf16 v[108:111], v[166:169], v[182:185], v[108:111]
	v_mfma_f32_16x16x32_bf16 v[104:107], v[174:177], v[182:185], v[104:107]
	v_mfma_f32_16x16x32_bf16 v[92:95], v[166:169], v[190:193], v[92:95]
	v_mfma_f32_16x16x32_bf16 v[88:91], v[174:177], v[190:193], v[88:91]
	v_mfma_f32_16x16x32_bf16 v[76:79], v[166:169], v[202:205], v[76:79]
	v_mfma_f32_16x16x32_bf16 v[72:75], v[174:177], v[202:205], v[72:75]
	v_mfma_f32_16x16x32_bf16 v[68:71], v[166:169], v[220:223], v[68:71]
	v_mfma_f32_16x16x32_bf16 v[64:67], v[174:177], v[220:223], v[64:67]
	v_mfma_f32_16x16x32_bf16 v[108:111], v[170:173], v[186:189], v[108:111]
	v_mfma_f32_16x16x32_bf16 v[104:107], v[178:181], v[186:189], v[104:107]
	v_mfma_f32_16x16x32_bf16 v[92:95], v[170:173], v[198:201], v[92:95]
	v_mfma_f32_16x16x32_bf16 v[88:91], v[178:181], v[198:201], v[88:91]
	v_mfma_f32_16x16x32_bf16 v[76:79], v[170:173], v[216:219], v[76:79]
	v_mfma_f32_16x16x32_bf16 v[72:75], v[178:181], v[216:219], v[72:75]
	v_mfma_f32_16x16x32_bf16 v[68:71], v[170:173], v[224:227], v[68:71]
	v_mfma_f32_16x16x32_bf16 v[64:67], v[178:181], v[224:227], v[64:67]
	s_barrier
; #define PG8_STAGE(bufoff, gbase, voff) do { _Pragma("unroll") for (int _i = 0; _i < 2; ++_i) \
;         __builtin_amdgcn_global_load_lds((const unsigned*)((const char*)(gbase) + (voff)[_i]), (LAS unsigned*)(lds + (bufoff) + ldsw + _i * 8192), 16, 0, 0); } while (0)
; #define PG8_LDA(dst, b, h) do { _Pragma("unroll") for (int m = 0; m < 4; ++m) _Pragma("unroll") for (int k = 0; k < 2; ++k) dst[m][k] = *(const LAS bf16x8*)(lds + PG8_SA(b, h) + aoff + m * 2048 + k * 1024); } while (0)
; #define PG8_MMA(ai, bj, At, Bt) do { __builtin_amdgcn_s_setprio(1); _Pragma("unroll") for (int m = 0; m < 4; ++m) _Pragma("unroll") for (int n = 0; n < 2; ++n) _Pragma("unroll") for (int k = 0; k < 2; ++k) \
;         acc[ai][bj][m][n] = __builtin_amdgcn_mfma_f32_16x16x32_bf16(Bt[n][k], At[m][k], acc[ai][bj][m][n], 0, 0, 0); __builtin_amdgcn_s_setprio(0); } while (0)
; #define PG8_WAIT_V(n) asm volatile("s_waitcnt vmcnt(" #n ")" ::: "memory")
; #define PG8_WAIT_L(n) asm volatile("s_waitcnt lgkmcnt(" #n ")" ::: "memory")
; #define PG8_BAR __builtin_amdgcn_s_barrier()
; #define PG8_SCHED __builtin_amdgcn_sched_barrier(0)
; template <class Epi, bool ALIGN_EPI, bool SP2 = PG8_SP2_DEFAULT>
; __device__ __forceinline__ void gemm_phase(LAS unsigned char* lds, const Gemm g, const StaticOrder& S, const Epi& E) {
;     ...
;         for (int t = 0; t < nt; t += 2) {
;     ...
;             PG8_LDA(At, 1, 1); PG8_STAGE(PG8_SB(1, 0), b3, voffB); PG8_STAGE(PG8_SB(1, 1), b3 + hstepB, voffB); PG8_STAGE(PG8_SA(1, 0), a3, voffA);
;             PG8_WAIT_V(8); PG8_WAIT_L(0); PG8_BAR; PG8_MMA(1, 0, At, B0); PG8_MMA(1, 1, At, B1); PG8_BAR; PG8_SCHED;
;     ...
;         if constexpr (ALIGN_EPI) { if (wr == 0) PG8_BAR; }
	s_setprio 0
	s_add_i32 s22, s45, s24
	v_lshl_add_u64 v[206:207], v[206:207], 0, s[4:5]
	s_mov_b32 m0, s22
	ds_read_b128 v[182:185], v149 offset:49152
	ds_read_b128 v[186:189], v149 offset:50176
	ds_read_b128 v[190:193], v149 offset:51200
	ds_read_b128 v[198:201], v149 offset:52224
	ds_read_b128 v[202:205], v149 offset:53248
	ds_read_b128 v[216:219], v149 offset:54272
	ds_read_b128 v[220:223], v149 offset:55296
	ds_read_b128 v[224:227], v149 offset:56320
	global_load_lds_dwordx4 v[206:207], off
	s_add_i32 m0, s22, 0x2000
	s_add_u32 s20, s20, 0x100080
	v_lshl_add_u64 v[206:207], v[210:211], 0, s[4:5]
	s_addc_u32 s21, s21, 0
	s_add_i32 s22, s46, s24
	global_load_lds_dwordx4 v[206:207], off
	v_lshl_add_u64 v[206:207], s[20:21], 0, v[132:133]
	s_mov_b32 m0, s22
	s_nop 0
	global_load_lds_dwordx4 v[206:207], off
	v_lshl_add_u64 v[206:207], s[20:21], 0, v[128:129]
	s_add_i32 m0, s22, 0x2000
	s_nop 0
	global_load_lds_dwordx4 v[206:207], off
	v_lshl_add_u64 v[206:207], v[228:229], 0, s[4:5]
	s_mov_b32 m0, s33
	s_nop 0
	global_load_lds_dwordx4 v[206:207], off
	v_lshl_add_u64 v[206:207], v[230:231], 0, s[4:5]
	s_mov_b32 m0, s34
	s_nop 0
	global_load_lds_dwordx4 v[206:207], off
	s_waitcnt vmcnt(8)
	s_waitcnt lgkmcnt(0)
	s_setprio 1
	s_barrier
	v_mfma_f32_16x16x32_bf16 v[60:63], v[150:153], v[182:185], v[60:63]
	v_mfma_f32_16x16x32_bf16 v[56:59], v[158:161], v[182:185], v[56:59]
	v_mfma_f32_16x16x32_bf16 v[52:55], v[150:153], v[190:193], v[52:55]
	v_mfma_f32_16x16x32_bf16 v[48:51], v[158:161], v[190:193], v[48:51]
	v_mfma_f32_16x16x32_bf16 v[36:39], v[150:153], v[202:205], v[36:39]
	v_mfma_f32_16x16x32_bf16 v[32:35], v[158:161], v[202:205], v[32:35]
	v_mfma_f32_16x16x32_bf16 v[20:23], v[150:153], v[220:223], v[20:23]
	v_mfma_f32_16x16x32_bf16 v[16:19], v[158:161], v[220:223], v[16:19]
	v_mfma_f32_16x16x32_bf16 v[60:63], v[154:157], v[186:189], v[60:63]
	v_mfma_f32_16x16x32_bf16 v[56:59], v[162:165], v[186:189], v[56:59]
	v_mfma_f32_16x16x32_bf16 v[52:55], v[154:157], v[198:201], v[52:55]
	v_mfma_f32_16x16x32_bf16 v[48:51], v[162:165], v[198:201], v[48:51]
	v_mfma_f32_16x16x32_bf16 v[36:39], v[154:157], v[216:219], v[36:39]
	v_mfma_f32_16x16x32_bf16 v[32:35], v[162:165], v[216:219], v[32:35]
	v_mfma_f32_16x16x32_bf16 v[20:23], v[154:157], v[224:227], v[20:23]
	v_mfma_f32_16x16x32_bf16 v[16:19], v[162:165], v[224:227], v[16:19]
	v_mfma_f32_16x16x32_bf16 v[44:47], v[166:169], v[182:185], v[44:47]
	v_mfma_f32_16x16x32_bf16 v[40:43], v[174:177], v[182:185], v[40:43]
	v_mfma_f32_16x16x32_bf16 v[28:31], v[166:169], v[190:193], v[28:31]
	v_mfma_f32_16x16x32_bf16 v[24:27], v[174:177], v[190:193], v[24:27]
	v_mfma_f32_16x16x32_bf16 v[12:15], v[166:169], v[202:205], v[12:15]
	v_mfma_f32_16x16x32_bf16 v[8:11], v[174:177], v[202:205], v[8:11]
	v_mfma_f32_16x16x32_bf16 v[4:7], v[166:169], v[220:223], v[4:7]
	v_mfma_f32_16x16x32_bf16 v[0:3], v[174:177], v[220:223], v[0:3]
	v_mfma_f32_16x16x32_bf16 v[44:47], v[170:173], v[186:189], v[44:47]
	v_mfma_f32_16x16x32_bf16 v[40:43], v[178:181], v[186:189], v[40:43]
	v_mfma_f32_16x16x32_bf16 v[28:31], v[170:173], v[198:201], v[28:31]
	v_mfma_f32_16x16x32_bf16 v[24:27], v[178:181], v[198:201], v[24:27]
	v_mfma_f32_16x16x32_bf16 v[12:15], v[170:173], v[216:219], v[12:15]
	v_mfma_f32_16x16x32_bf16 v[8:11], v[178:181], v[216:219], v[8:11]
	v_mfma_f32_16x16x32_bf16 v[4:7], v[170:173], v[224:227], v[4:7]
	v_mfma_f32_16x16x32_bf16 v[0:3], v[178:181], v[224:227], v[0:3]
	s_barrier
	s_setprio 0
	s_add_i32 s44, s44, 2
	s_add_u32 s18, s18, 0x100
	s_addc_u32 s19, s19, 0
	s_add_u32 s42, s42, 0x100
	s_addc_u32 s43, s43, 0
	s_cmp_gt_u32 s44, 61
	s_cbranch_scc0 .LBB0_250
	s_and_b64 vcc, exec, s[6:7]
	s_cbranch_vccz .LBB0_253
	s_barrier

; #define PG8_STAGE(bufoff, gbase, voff) do { _Pragma("unroll") for (int _i = 0; _i < 2; ++_i) \
;         __builtin_amdgcn_global_load_lds((const unsigned*)((const char*)(gbase) + (voff)[_i]), (LAS unsigned*)(lds + (bufoff) + ldsw + _i * 8192), 16, 0, 0); } while (0)
; #define PG8_LDA(dst, b, h) do { _Pragma("unroll") for (int m = 0; m < 4; ++m) _Pragma("unroll") for (int k = 0; k < 2; ++k) dst[m][k] = *(const LAS bf16x8*)(lds + PG8_SA(b, h) + aoff + m * 2048 + k * 1024); } while (0)
; #define PG8_LDB(dst, b, h) do { _Pragma("unroll") for (int n = 0; n < 2; ++n) _Pragma("unroll") for (int k = 0; k < 2; ++k) dst[n][k] = *(const LAS bf16x8*)(lds + PG8_SB(b, h) + boff + n * 2048 + k * 1024); } while (0)
; #define PG8_MMA(ai, bj, At, Bt) do { __builtin_amdgcn_s_setprio(1); _Pragma("unroll") for (int m = 0; m < 4; ++m) _Pragma("unroll") for (int n = 0; n < 2; ++n) _Pragma("unroll") for (int k = 0; k < 2; ++k) \
;         acc[ai][bj][m][n] = __builtin_amdgcn_mfma_f32_16x16x32_bf16(Bt[n][k], At[m][k], acc[ai][bj][m][n], 0, 0, 0); __builtin_amdgcn_s_setprio(0); } while (0)
; #define PG8_WAIT_V(n) asm volatile("s_waitcnt vmcnt(" #n ")" ::: "memory")
; #define PG8_WAIT_L(n) asm volatile("s_waitcnt lgkmcnt(" #n ")" ::: "memory")
; #define PG8_BAR __builtin_amdgcn_s_barrier()
; #define PG8_SCHED __builtin_amdgcn_sched_barrier(0)
; template <class Epi, bool ALIGN_EPI, bool SP2 = PG8_SP2_DEFAULT>
; __device__ __forceinline__ void gemm_phase(LAS unsigned char* lds, const Gemm g, const StaticOrder& S, const Epi& E) {
;     ...
;             const bool last = (t == nt - 2);
;             const char* a1 = cA + (size_t)(t + 1) * kstep;
;             const char* a2 = last ? nA : cA + (size_t)(t + 2) * kstep; const char* b2 = last ? nB : cB + (size_t)(t + 2) * kstep;
;             const char* a3 = a2 + kstep; const char* b3 = b2 + kstep;
;             if constexpr (SP2) {
;             PG8_LDB(B0, 0, 0); PG8_LDB(B1, 0, 1); PG8_SCHED; PG8_LDA(At, 0, 0); PG8_STAGE(PG8_SA(1, 1), a1 + hstepA, voffA);
;             PG8_WAIT_V(8); PG8_WAIT_L(0); PG8_BAR; PG8_MMA(0, 0, At, B0); PG8_MMA(0, 1, At, B1); PG8_BAR; PG8_SCHED;
;             PG8_LDA(At, 0, 1); PG8_STAGE(PG8_SB(0, 0), b2, voffB); PG8_STAGE(PG8_SB(0, 1), b2 + hstepB, voffB); PG8_STAGE(PG8_SA(0, 0), a2, voffA);
.LBB0_428:
	ds_read_b128 v[128:131], v165
	ds_read_b128 v[132:135], v165 offset:1024
	ds_read_b128 v[136:139], v165 offset:2048
	ds_read_b128 v[140:143], v165 offset:3072
	ds_read_b128 v[168:171], v166
	ds_read_b128 v[172:175], v166 offset:1024
	ds_read_b128 v[176:179], v166 offset:2048
	ds_read_b128 v[180:183], v166 offset:3072
	s_add_u32 s24, s22, 0xfffe0080
	s_addc_u32 s25, s23, -1
	s_cmp_eq_u32 s51, 4
	s_cselect_b32 s27, s15, s25
	s_cselect_b32 s26, s47, s24
	s_cselect_b32 s25, s13, s50
	s_cselect_b32 s24, s48, s49
	v_lshl_add_u64 v[160:161], s[22:23], 0, v[152:153]
	s_add_i32 m0, s21, 0xc000
	ds_read_b128 v[184:187], v167
	ds_read_b128 v[188:191], v167 offset:1024
	ds_read_b128 v[198:201], v167 offset:2048
	ds_read_b128 v[202:205], v167 offset:3072
	ds_read_b128 v[216:219], v167 offset:4096
	ds_read_b128 v[220:223], v167 offset:5120
	ds_read_b128 v[224:227], v167 offset:6144
	ds_read_b128 v[228:231], v167 offset:7168
	global_load_lds_dwordx4 v[160:161], off
	v_lshl_add_u64 v[160:161], s[22:23], 0, v[154:155]
	s_add_i32 m0, s21, 0xe000
	s_nop 0
	global_load_lds_dwordx4 v[160:161], off
	s_waitcnt vmcnt(8)
	s_waitcnt lgkmcnt(0)
	s_setprio 1
	s_barrier
	v_mfma_f32_16x16x32_bf16 v[124:127], v[128:131], v[184:187], v[124:127]
	v_mfma_f32_16x16x32_bf16 v[120:123], v[136:139], v[184:187], v[120:123]
	v_mfma_f32_16x16x32_bf16 v[116:119], v[128:131], v[198:201], v[116:119]
	v_mfma_f32_16x16x32_bf16 v[112:115], v[136:139], v[198:201], v[112:115]
	v_mfma_f32_16x16x32_bf16 v[108:111], v[128:131], v[216:219], v[108:111]
	v_mfma_f32_16x16x32_bf16 v[100:103], v[136:139], v[216:219], v[100:103]
	v_mfma_f32_16x16x32_bf16 v[80:83], v[128:131], v[224:227], v[80:83]
	v_mfma_f32_16x16x32_bf16 v[72:75], v[136:139], v[224:227], v[72:75]
	v_mfma_f32_16x16x32_bf16 v[124:127], v[132:135], v[188:191], v[124:127]
	v_mfma_f32_16x16x32_bf16 v[120:123], v[140:143], v[188:191], v[120:123]
	v_mfma_f32_16x16x32_bf16 v[116:119], v[132:135], v[202:205], v[116:119]
	v_mfma_f32_16x16x32_bf16 v[112:115], v[140:143], v[202:205], v[112:115]
	v_mfma_f32_16x16x32_bf16 v[108:111], v[132:135], v[220:223], v[108:111]
	v_mfma_f32_16x16x32_bf16 v[100:103], v[140:143], v[220:223], v[100:103]
	v_mfma_f32_16x16x32_bf16 v[80:83], v[132:135], v[228:231], v[80:83]
	v_mfma_f32_16x16x32_bf16 v[72:75], v[140:143], v[228:231], v[72:75]
	v_mfma_f32_16x16x32_bf16 v[104:107], v[168:171], v[184:187], v[104:107]
	v_mfma_f32_16x16x32_bf16 v[96:99], v[176:179], v[184:187], v[96:99]
	v_mfma_f32_16x16x32_bf16 v[92:95], v[168:171], v[198:201], v[92:95]
	v_mfma_f32_16x16x32_bf16 v[88:91], v[176:179], v[198:201], v[88:91]
	v_mfma_f32_16x16x32_bf16 v[84:87], v[168:171], v[216:219], v[84:87]
	v_mfma_f32_16x16x32_bf16 v[76:79], v[176:179], v[216:219], v[76:79]
	v_mfma_f32_16x16x32_bf16 v[68:71], v[168:171], v[224:227], v[68:71]
	v_mfma_f32_16x16x32_bf16 v[64:67], v[176:179], v[224:227], v[64:67]
	v_mfma_f32_16x16x32_bf16 v[104:107], v[172:175], v[188:191], v[104:107]
	v_mfma_f32_16x16x32_bf16 v[96:99], v[180:183], v[188:191], v[96:99]
	v_mfma_f32_16x16x32_bf16 v[92:95], v[172:175], v[202:205], v[92:95]
	v_mfma_f32_16x16x32_bf16 v[88:91], v[180:183], v[202:205], v[88:91]
	v_mfma_f32_16x16x32_bf16 v[84:87], v[172:175], v[220:223], v[84:87]
	v_mfma_f32_16x16x32_bf16 v[76:79], v[180:183], v[220:223], v[76:79]
	v_mfma_f32_16x16x32_bf16 v[68:71], v[172:175], v[228:231], v[68:71]
	v_mfma_f32_16x16x32_bf16 v[64:67], v[180:183], v[228:231], v[64:67]
	s_barrier
	s_setprio 0
	s_add_i32 s52, s40, s29
	v_lshl_add_u64 v[160:161], s[24:25], 0, v[146:147]
	s_mov_b32 m0, s52
	ds_read_b128 v[184:187], v167 offset:16384
	ds_read_b128 v[188:191], v167 offset:17408
	ds_read_b128 v[198:201], v167 offset:18432
	ds_read_b128 v[202:205], v167 offset:19456
	ds_read_b128 v[216:219], v167 offset:20480
	ds_read_b128 v[220:223], v167 offset:21504
	ds_read_b128 v[224:227], v167 offset:22528
	ds_read_b128 v[228:231], v167 offset:23552
	global_load_lds_dwordx4 v[160:161], off
	s_add_i32 m0, s52, 0x2000
	s_add_u32 s52, s24, 0x20000
	v_lshl_add_u64 v[192:193], s[24:25], 0, v[150:151]
	s_addc_u32 s53, s25, 0
	s_add_i32 s54, s41, s29
	global_load_lds_dwordx4 v[192:193], off
	v_lshl_add_u64 v[206:207], s[52:53], 0, v[146:147]
	s_mov_b32 m0, s54
	v_lshl_add_u64 v[210:211], s[26:27], 0, v[148:149]
	global_load_lds_dwordx4 v[206:207], off
	v_lshl_add_u64 v[206:207], s[52:53], 0, v[150:151]
	s_add_i32 m0, s54, 0x2000
	s_nop 0
	global_load_lds_dwordx4 v[206:207], off
	v_lshl_add_u64 v[206:207], s[26:27], 0, v[144:145]
	s_mov_b32 m0, s21
	s_nop 0
	global_load_lds_dwordx4 v[206:207], off
	s_mov_b32 m0, s30
	s_nop 0
	global_load_lds_dwordx4 v[210:211], off
	s_waitcnt vmcnt(8)
	s_waitcnt lgkmcnt(0)
	s_setprio 1
	s_barrier
; #define PG8_STAGE(bufoff, gbase, voff) do { _Pragma("unroll") for (int _i = 0; _i < 2; ++_i) \
;         __builtin_amdgcn_global_load_lds((const unsigned*)((const char*)(gbase) + (voff)[_i]), (LAS unsigned*)(lds + (bufoff) + ldsw + _i * 8192), 16, 0, 0); } while (0)
; #define PG8_LDA(dst, b, h) do { _Pragma("unroll") for (int m = 0; m < 4; ++m) _Pragma("unroll") for (int k = 0; k < 2; ++k) dst[m][k] = *(const LAS bf16x8*)(lds + PG8_SA(b, h) + aoff + m * 2048 + k * 1024); } while (0)
; #define PG8_LDB(dst, b, h) do { _Pragma("unroll") for (int n = 0; n < 2; ++n) _Pragma("unroll") for (int k = 0; k < 2; ++k) dst[n][k] = *(const LAS bf16x8*)(lds + PG8_SB(b, h) + boff + n * 2048 + k * 1024); } while (0)
; #define PG8_MMA(ai, bj, At, Bt) do { __builtin_amdgcn_s_setprio(1); _Pragma("unroll") for (int m = 0; m < 4; ++m) _Pragma("unroll") for (int n = 0; n < 2; ++n) _Pragma("unroll") for (int k = 0; k < 2; ++k) \
;         acc[ai][bj][m][n] = __builtin_amdgcn_mfma_f32_16x16x32_bf16(Bt[n][k], At[m][k], acc[ai][bj][m][n], 0, 0, 0); __builtin_amdgcn_s_setprio(0); } while (0)
; #define PG8_WAIT_V(n) asm volatile("s_waitcnt vmcnt(" #n ")" ::: "memory")
; #define PG8_WAIT_L(n) asm volatile("s_waitcnt lgkmcnt(" #n ")" ::: "memory")
; #define PG8_BAR __builtin_amdgcn_s_barrier()
; #define PG8_SCHED __builtin_amdgcn_sched_barrier(0)
; template <class Epi, bool ALIGN_EPI, bool SP2 = PG8_SP2_DEFAULT>
; __device__ __forceinline__ void gemm_phase(LAS unsigned char* lds, const Gemm g, const StaticOrder& S, const Epi& E) {
;     ...
;             PG8_WAIT_V(8); PG8_WAIT_L(0); PG8_BAR; PG8_MMA(1, 0, At, B0); PG8_MMA(1, 1, At, B1); PG8_BAR; PG8_SCHED;
;             PG8_LDB(B0, 1, 0); PG8_LDB(B1, 1, 1); PG8_SCHED; PG8_LDA(At, 1, 0); PG8_STAGE(PG8_SA(0, 1), a2 + hstepA, voffA);
;             PG8_WAIT_V(8); PG8_WAIT_L(0); PG8_BAR; PG8_MMA(0, 0, At, B0); PG8_MMA(0, 1, At, B1); PG8_BAR; PG8_SCHED;
	v_mfma_f32_16x16x32_bf16 v[60:63], v[128:131], v[184:187], v[60:63]
	v_mfma_f32_16x16x32_bf16 v[56:59], v[136:139], v[184:187], v[56:59]
	v_mfma_f32_16x16x32_bf16 v[52:55], v[128:131], v[198:201], v[52:55]
	v_mfma_f32_16x16x32_bf16 v[44:47], v[136:139], v[198:201], v[44:47]
	v_mfma_f32_16x16x32_bf16 v[36:39], v[128:131], v[216:219], v[36:39]
	v_mfma_f32_16x16x32_bf16 v[28:31], v[136:139], v[216:219], v[28:31]
	v_mfma_f32_16x16x32_bf16 v[20:23], v[128:131], v[224:227], v[20:23]
	v_mfma_f32_16x16x32_bf16 v[12:15], v[136:139], v[224:227], v[12:15]
	v_mfma_f32_16x16x32_bf16 v[60:63], v[132:135], v[188:191], v[60:63]
	v_mfma_f32_16x16x32_bf16 v[56:59], v[140:143], v[188:191], v[56:59]
	v_mfma_f32_16x16x32_bf16 v[52:55], v[132:135], v[202:205], v[52:55]
	v_mfma_f32_16x16x32_bf16 v[44:47], v[140:143], v[202:205], v[44:47]
	v_mfma_f32_16x16x32_bf16 v[36:39], v[132:135], v[220:223], v[36:39]
	v_mfma_f32_16x16x32_bf16 v[28:31], v[140:143], v[220:223], v[28:31]
	v_mfma_f32_16x16x32_bf16 v[20:23], v[132:135], v[228:231], v[20:23]
	v_mfma_f32_16x16x32_bf16 v[12:15], v[140:143], v[228:231], v[12:15]
	v_mfma_f32_16x16x32_bf16 v[48:51], v[168:171], v[184:187], v[48:51]
	v_mfma_f32_16x16x32_bf16 v[40:43], v[176:179], v[184:187], v[40:43]
	v_mfma_f32_16x16x32_bf16 v[32:35], v[168:171], v[198:201], v[32:35]
	v_mfma_f32_16x16x32_bf16 v[24:27], v[176:179], v[198:201], v[24:27]
	v_mfma_f32_16x16x32_bf16 v[16:19], v[168:171], v[216:219], v[16:19]
	v_mfma_f32_16x16x32_bf16 v[8:11], v[176:179], v[216:219], v[8:11]
	v_mfma_f32_16x16x32_bf16 v[4:7], v[168:171], v[224:227], v[4:7]
	v_mfma_f32_16x16x32_bf16 v[0:3], v[176:179], v[224:227], v[0:3]
	v_mfma_f32_16x16x32_bf16 v[48:51], v[172:175], v[188:191], v[48:51]
	v_mfma_f32_16x16x32_bf16 v[40:43], v[180:183], v[188:191], v[40:43]
	v_mfma_f32_16x16x32_bf16 v[32:35], v[172:175], v[202:205], v[32:35]
	v_mfma_f32_16x16x32_bf16 v[24:27], v[180:183], v[202:205], v[24:27]
	v_mfma_f32_16x16x32_bf16 v[16:19], v[172:175], v[220:223], v[16:19]
	v_mfma_f32_16x16x32_bf16 v[8:11], v[180:183], v[220:223], v[8:11]
	v_mfma_f32_16x16x32_bf16 v[4:7], v[172:175], v[228:231], v[4:7]
	v_mfma_f32_16x16x32_bf16 v[0:3], v[180:183], v[228:231], v[0:3]
	s_barrier
	s_setprio 0
	s_add_i32 s52, 0, 0x18000
	s_add_i32 s53, 0, 0x1c000
	v_add_u32_e32 v140, s52, v163
	v_add_u32_e32 v180, s53, v163
	ds_read_b128 v[128:131], v140
	ds_read_b128 v[132:135], v140 offset:1024
	ds_read_b128 v[136:139], v140 offset:2048
	ds_read_b128 v[140:143], v140 offset:3072
	ds_read_b128 v[168:171], v180
	ds_read_b128 v[172:175], v180 offset:1024
	ds_read_b128 v[176:179], v180 offset:2048
	ds_read_b128 v[180:183], v180 offset:3072
	s_add_u32 s26, s26, 0x20000
	s_addc_u32 s27, s27, 0
	s_mov_b32 m0, s31
	v_lshl_add_u64 v[232:233], s[26:27], 0, v[144:145]
	ds_read_b128 v[184:187], v167 offset:32768
	ds_read_b128 v[188:191], v167 offset:33792
	ds_read_b128 v[198:201], v167 offset:34816
	ds_read_b128 v[202:205], v167 offset:35840
	ds_read_b128 v[216:219], v167 offset:36864
	ds_read_b128 v[220:223], v167 offset:37888
	ds_read_b128 v[224:227], v167 offset:38912
	ds_read_b128 v[228:231], v167 offset:39936
	global_load_lds_dwordx4 v[232:233], off
	v_lshl_add_u64 v[232:233], s[26:27], 0, v[148:149]
	s_mov_b32 m0, s34
	s_nop 0
	global_load_lds_dwordx4 v[232:233], off
	s_waitcnt vmcnt(8)
	s_waitcnt lgkmcnt(0)
	s_setprio 1
	s_barrier
	v_mfma_f32_16x16x32_bf16 v[124:127], v[128:131], v[184:187], v[124:127]
	v_mfma_f32_16x16x32_bf16 v[120:123], v[136:139], v[184:187], v[120:123]
	v_mfma_f32_16x16x32_bf16 v[116:119], v[128:131], v[198:201], v[116:119]
	v_mfma_f32_16x16x32_bf16 v[112:115], v[136:139], v[198:201], v[112:115]
	v_mfma_f32_16x16x32_bf16 v[108:111], v[128:131], v[216:219], v[108:111]
	v_mfma_f32_16x16x32_bf16 v[100:103], v[136:139], v[216:219], v[100:103]
	v_mfma_f32_16x16x32_bf16 v[80:83], v[128:131], v[224:227], v[80:83]
	v_mfma_f32_16x16x32_bf16 v[72:75], v[136:139], v[224:227], v[72:75]
	v_mfma_f32_16x16x32_bf16 v[124:127], v[132:135], v[188:191], v[124:127]
	v_mfma_f32_16x16x32_bf16 v[120:123], v[140:143], v[188:191], v[120:123]
	v_mfma_f32_16x16x32_bf16 v[116:119], v[132:135], v[202:205], v[116:119]
	v_mfma_f32_16x16x32_bf16 v[112:115], v[140:143], v[202:205], v[112:115]
	v_mfma_f32_16x16x32_bf16 v[108:111], v[132:135], v[220:223], v[108:111]
	v_mfma_f32_16x16x32_bf16 v[100:103], v[140:143], v[220:223], v[100:103]
	v_mfma_f32_16x16x32_bf16 v[80:83], v[132:135], v[228:231], v[80:83]
	v_mfma_f32_16x16x32_bf16 v[72:75], v[140:143], v[228:231], v[72:75]
	v_mfma_f32_16x16x32_bf16 v[104:107], v[168:171], v[184:187], v[104:107]
	v_mfma_f32_16x16x32_bf16 v[96:99], v[176:179], v[184:187], v[96:99]
	v_mfma_f32_16x16x32_bf16 v[92:95], v[168:171], v[198:201], v[92:95]
	v_mfma_f32_16x16x32_bf16 v[88:91], v[176:179], v[198:201], v[88:91]
	v_mfma_f32_16x16x32_bf16 v[84:87], v[168:171], v[216:219], v[84:87]
	v_mfma_f32_16x16x32_bf16 v[76:79], v[176:179], v[216:219], v[76:79]
	v_mfma_f32_16x16x32_bf16 v[68:71], v[168:171], v[224:227], v[68:71]
	v_mfma_f32_16x16x32_bf16 v[64:67], v[176:179], v[224:227], v[64:67]
	v_mfma_f32_16x16x32_bf16 v[104:107], v[172:175], v[188:191], v[104:107]
	v_mfma_f32_16x16x32_bf16 v[96:99], v[180:183], v[188:191], v[96:99]
	v_mfma_f32_16x16x32_bf16 v[92:95], v[172:175], v[202:205], v[92:95]
	v_mfma_f32_16x16x32_bf16 v[88:91], v[180:183], v[202:205], v[88:91]
	v_mfma_f32_16x16x32_bf16 v[84:87], v[172:175], v[220:223], v[84:87]
	v_mfma_f32_16x16x32_bf16 v[76:79], v[180:183], v[220:223], v[76:79]
	v_mfma_f32_16x16x32_bf16 v[68:71], v[172:175], v[228:231], v[68:71]
	v_mfma_f32_16x16x32_bf16 v[64:67], v[180:183], v[228:231], v[64:67]
	s_barrier
; #define PG8_STAGE(bufoff, gbase, voff) do { _Pragma("unroll") for (int _i = 0; _i < 2; ++_i) \
;         __builtin_amdgcn_global_load_lds((const unsigned*)((const char*)(gbase) + (voff)[_i]), (LAS unsigned*)(lds + (bufoff) + ldsw + _i * 8192), 16, 0, 0); } while (0)
; #define PG8_LDA(dst, b, h) do { _Pragma("unroll") for (int m = 0; m < 4; ++m) _Pragma("unroll") for (int k = 0; k < 2; ++k) dst[m][k] = *(const LAS bf16x8*)(lds + PG8_SA(b, h) + aoff + m * 2048 + k * 1024); } while (0)
; #define PG8_MMA(ai, bj, At, Bt) do { __builtin_amdgcn_s_setprio(1); _Pragma("unroll") for (int m = 0; m < 4; ++m) _Pragma("unroll") for (int n = 0; n < 2; ++n) _Pragma("unroll") for (int k = 0; k < 2; ++k) \
;         acc[ai][bj][m][n] = __builtin_amdgcn_mfma_f32_16x16x32_bf16(Bt[n][k], At[m][k], acc[ai][bj][m][n], 0, 0, 0); __builtin_amdgcn_s_setprio(0); } while (0)
; #define PG8_WAIT_V(n) asm volatile("s_waitcnt vmcnt(" #n ")" ::: "memory")
; #define PG8_WAIT_L(n) asm volatile("s_waitcnt lgkmcnt(" #n ")" ::: "memory")
; #define PG8_BAR __builtin_amdgcn_s_barrier()
; #define PG8_SCHED __builtin_amdgcn_sched_barrier(0)
; template <class Epi, bool ALIGN_EPI, bool SP2 = PG8_SP2_DEFAULT>
; __device__ __forceinline__ void gemm_phase(LAS unsigned char* lds, const Gemm g, const StaticOrder& S, const Epi& E) {
;     ...
;         for (int t = 0; t < nt; t += 2) {
;     ...
;             PG8_LDA(At, 1, 1); PG8_STAGE(PG8_SB(1, 0), b3, voffB); PG8_STAGE(PG8_SB(1, 1), b3 + hstepB, voffB); PG8_STAGE(PG8_SA(1, 0), a3, voffA);
;             PG8_WAIT_V(8); PG8_WAIT_L(0); PG8_BAR; PG8_MMA(1, 0, At, B0); PG8_MMA(1, 1, At, B1); PG8_BAR; PG8_SCHED;
;     ...
;         if constexpr (ALIGN_EPI) { if (wr == 0) PG8_BAR; }
	s_setprio 0
	s_add_i32 s26, s52, s29
	v_lshl_add_u64 v[160:161], v[160:161], 0, s[4:5]
	s_mov_b32 m0, s26
	ds_read_b128 v[184:187], v167 offset:49152
	ds_read_b128 v[188:191], v167 offset:50176
	ds_read_b128 v[198:201], v167 offset:51200
	ds_read_b128 v[202:205], v167 offset:52224
	ds_read_b128 v[216:219], v167 offset:53248
	ds_read_b128 v[220:223], v167 offset:54272
	ds_read_b128 v[224:227], v167 offset:55296
	ds_read_b128 v[228:231], v167 offset:56320
	global_load_lds_dwordx4 v[160:161], off
	s_add_i32 m0, s26, 0x2000
	s_add_u32 s24, s24, 0x20080
	v_lshl_add_u64 v[160:161], v[192:193], 0, s[4:5]
	s_addc_u32 s25, s25, 0
	s_add_i32 s26, s53, s29
	global_load_lds_dwordx4 v[160:161], off
	v_lshl_add_u64 v[160:161], s[24:25], 0, v[146:147]
	s_mov_b32 m0, s26
	s_nop 0
	global_load_lds_dwordx4 v[160:161], off
	v_lshl_add_u64 v[160:161], s[24:25], 0, v[150:151]
	s_add_i32 m0, s26, 0x2000
	s_nop 0
	global_load_lds_dwordx4 v[160:161], off
	v_lshl_add_u64 v[160:161], v[206:207], 0, s[4:5]
	s_mov_b32 m0, s36
	s_nop 0
	global_load_lds_dwordx4 v[160:161], off
	v_lshl_add_u64 v[160:161], v[210:211], 0, s[4:5]
	s_mov_b32 m0, s37
	s_nop 0
	global_load_lds_dwordx4 v[160:161], off
	s_waitcnt vmcnt(8)
	s_waitcnt lgkmcnt(0)
	s_setprio 1
	s_barrier
	v_mfma_f32_16x16x32_bf16 v[60:63], v[128:131], v[184:187], v[60:63]
	v_mfma_f32_16x16x32_bf16 v[56:59], v[136:139], v[184:187], v[56:59]
	v_mfma_f32_16x16x32_bf16 v[52:55], v[128:131], v[198:201], v[52:55]
	v_mfma_f32_16x16x32_bf16 v[44:47], v[136:139], v[198:201], v[44:47]
	v_mfma_f32_16x16x32_bf16 v[36:39], v[128:131], v[216:219], v[36:39]
	v_mfma_f32_16x16x32_bf16 v[28:31], v[136:139], v[216:219], v[28:31]
	v_mfma_f32_16x16x32_bf16 v[20:23], v[128:131], v[224:227], v[20:23]
	v_mfma_f32_16x16x32_bf16 v[12:15], v[136:139], v[224:227], v[12:15]
	v_mfma_f32_16x16x32_bf16 v[60:63], v[132:135], v[188:191], v[60:63]
	v_mfma_f32_16x16x32_bf16 v[56:59], v[140:143], v[188:191], v[56:59]
	v_mfma_f32_16x16x32_bf16 v[52:55], v[132:135], v[202:205], v[52:55]
	v_mfma_f32_16x16x32_bf16 v[44:47], v[140:143], v[202:205], v[44:47]
	v_mfma_f32_16x16x32_bf16 v[36:39], v[132:135], v[220:223], v[36:39]
	v_mfma_f32_16x16x32_bf16 v[28:31], v[140:143], v[220:223], v[28:31]
	v_mfma_f32_16x16x32_bf16 v[20:23], v[132:135], v[228:231], v[20:23]
	v_mfma_f32_16x16x32_bf16 v[12:15], v[140:143], v[228:231], v[12:15]
	v_mfma_f32_16x16x32_bf16 v[48:51], v[168:171], v[184:187], v[48:51]
	v_mfma_f32_16x16x32_bf16 v[40:43], v[176:179], v[184:187], v[40:43]
	v_mfma_f32_16x16x32_bf16 v[32:35], v[168:171], v[198:201], v[32:35]
	v_mfma_f32_16x16x32_bf16 v[24:27], v[176:179], v[198:201], v[24:27]
	v_mfma_f32_16x16x32_bf16 v[16:19], v[168:171], v[216:219], v[16:19]
	v_mfma_f32_16x16x32_bf16 v[8:11], v[176:179], v[216:219], v[8:11]
	v_mfma_f32_16x16x32_bf16 v[4:7], v[168:171], v[224:227], v[4:7]
	v_mfma_f32_16x16x32_bf16 v[0:3], v[176:179], v[224:227], v[0:3]
	v_mfma_f32_16x16x32_bf16 v[48:51], v[172:175], v[188:191], v[48:51]
	v_mfma_f32_16x16x32_bf16 v[40:43], v[180:183], v[188:191], v[40:43]
	v_mfma_f32_16x16x32_bf16 v[32:35], v[172:175], v[202:205], v[32:35]
	v_mfma_f32_16x16x32_bf16 v[24:27], v[180:183], v[202:205], v[24:27]
	v_mfma_f32_16x16x32_bf16 v[16:19], v[172:175], v[220:223], v[16:19]
	v_mfma_f32_16x16x32_bf16 v[8:11], v[180:183], v[220:223], v[8:11]
	v_mfma_f32_16x16x32_bf16 v[4:7], v[172:175], v[228:231], v[4:7]
	v_mfma_f32_16x16x32_bf16 v[0:3], v[180:183], v[228:231], v[0:3]
	s_barrier
	s_setprio 0
	s_add_i32 s51, s51, 2
	s_add_u32 s22, s22, 0x100
	s_addc_u32 s23, s23, 0
	s_add_u32 s49, s49, 0x100
	s_addc_u32 s50, s50, 0
	s_cmp_gt_u32 s51, 5
	s_cbranch_scc0 .LBB0_428
	s_and_b64 vcc, exec, s[6:7]
	s_cbranch_vccz .LBB0_431
	s_barrier

; #define PG8_STAGE(bufoff, gbase, voff) do { _Pragma("unroll") for (int _i = 0; _i < 2; ++_i) \
;         __builtin_amdgcn_global_load_lds((const unsigned*)((const char*)(gbase) + (voff)[_i]), (LAS unsigned*)(lds + (bufoff) + ldsw + _i * 8192), 16, 0, 0); } while (0)
; #define PG8_LDA(dst, b, h) do { _Pragma("unroll") for (int m = 0; m < 4; ++m) _Pragma("unroll") for (int k = 0; k < 2; ++k) dst[m][k] = *(const LAS bf16x8*)(lds + PG8_SA(b, h) + aoff + m * 2048 + k * 1024); } while (0)
; #define PG8_LDB(dst, b, h) do { _Pragma("unroll") for (int n = 0; n < 2; ++n) _Pragma("unroll") for (int k = 0; k < 2; ++k) dst[n][k] = *(const LAS bf16x8*)(lds + PG8_SB(b, h) + boff + n * 2048 + k * 1024); } while (0)
; #define PG8_MMA(ai, bj, At, Bt) do { __builtin_amdgcn_s_setprio(1); _Pragma("unroll") for (int m = 0; m < 4; ++m) _Pragma("unroll") for (int n = 0; n < 2; ++n) _Pragma("unroll") for (int k = 0; k < 2; ++k) \
;         acc[ai][bj][m][n] = __builtin_amdgcn_mfma_f32_16x16x32_bf16(Bt[n][k], At[m][k], acc[ai][bj][m][n], 0, 0, 0); __builtin_amdgcn_s_setprio(0); } while (0)
; #define PG8_WAIT_V(n) asm volatile("s_waitcnt vmcnt(" #n ")" ::: "memory")
; #define PG8_WAIT_L(n) asm volatile("s_waitcnt lgkmcnt(" #n ")" ::: "memory")
; #define PG8_BAR __builtin_amdgcn_s_barrier()
; #define PG8_SCHED __builtin_amdgcn_sched_barrier(0)
; template <class Epi, bool ALIGN_EPI, bool SP2 = PG8_SP2_DEFAULT>
; __device__ __forceinline__ void gemm_phase(LAS unsigned char* lds, const Gemm g, const StaticOrder& S, const Epi& E) {
;     ...
;             const bool last = (t == nt - 2);
;             const char* a1 = cA + (size_t)(t + 1) * kstep;
;             const char* a2 = last ? nA : cA + (size_t)(t + 2) * kstep; const char* b2 = last ? nB : cB + (size_t)(t + 2) * kstep;
;             const char* a3 = a2 + kstep; const char* b3 = b2 + kstep;
;             if constexpr (SP2) {
;             PG8_LDB(B0, 0, 0); PG8_LDB(B1, 0, 1); PG8_SCHED; PG8_LDA(At, 0, 0); PG8_STAGE(PG8_SA(1, 1), a1 + hstepA, voffA);
;             PG8_WAIT_V(8); PG8_WAIT_L(0); PG8_BAR; PG8_MMA(0, 0, At, B0); PG8_MMA(0, 1, At, B1); PG8_BAR; PG8_SCHED;
;             PG8_LDA(At, 0, 1); PG8_STAGE(PG8_SB(0, 0), b2, voffB); PG8_STAGE(PG8_SB(0, 1), b2 + hstepB, voffB); PG8_STAGE(PG8_SA(0, 0), a2, voffA);
.LBB0_506:
	ds_read_b128 v[144:147], v151
	ds_read_b128 v[156:159], v151 offset:1024
	ds_read_b128 v[160:163], v151 offset:2048
	ds_read_b128 v[164:167], v151 offset:3072
	ds_read_b128 v[168:171], v152
	ds_read_b128 v[172:175], v152 offset:1024
	ds_read_b128 v[176:179], v152 offset:2048
	ds_read_b128 v[180:183], v152 offset:3072
	s_add_u32 s28, s26, 0xfff00080
	s_addc_u32 s29, s27, -1
	s_cmp_eq_u32 s50, 60
	s_cselect_b32 s31, s19, s29
	s_cselect_b32 s30, s25, s28
	s_cselect_b32 s29, s3, s49
	s_cselect_b32 s28, s47, s48
	v_lshl_add_u64 v[192:193], s[26:27], 0, v[136:137]
	s_add_i32 m0, s34, 0xc000
	ds_read_b128 v[184:187], v153
	ds_read_b128 v[188:191], v153 offset:1024
	ds_read_b128 v[198:201], v153 offset:2048
	ds_read_b128 v[202:205], v153 offset:3072
	ds_read_b128 v[216:219], v153 offset:4096
	ds_read_b128 v[220:223], v153 offset:5120
	ds_read_b128 v[224:227], v153 offset:6144
	ds_read_b128 v[228:231], v153 offset:7168
	global_load_lds_dwordx4 v[192:193], off
	v_lshl_add_u64 v[192:193], s[26:27], 0, v[138:139]
	s_add_i32 m0, s34, 0xe000
	s_nop 0
	global_load_lds_dwordx4 v[192:193], off
	s_waitcnt vmcnt(8)
	s_waitcnt lgkmcnt(0)
	s_setprio 1
	s_barrier
	v_mfma_f32_16x16x32_bf16 v[124:127], v[144:147], v[184:187], v[124:127]
	v_mfma_f32_16x16x32_bf16 v[120:123], v[160:163], v[184:187], v[120:123]
	v_mfma_f32_16x16x32_bf16 v[108:111], v[144:147], v[198:201], v[108:111]
	v_mfma_f32_16x16x32_bf16 v[104:107], v[160:163], v[198:201], v[104:107]
	v_mfma_f32_16x16x32_bf16 v[92:95], v[144:147], v[216:219], v[92:95]
	v_mfma_f32_16x16x32_bf16 v[88:91], v[160:163], v[216:219], v[88:91]
	v_mfma_f32_16x16x32_bf16 v[76:79], v[144:147], v[224:227], v[76:79]
	v_mfma_f32_16x16x32_bf16 v[72:75], v[160:163], v[224:227], v[72:75]
	v_mfma_f32_16x16x32_bf16 v[124:127], v[156:159], v[188:191], v[124:127]
	v_mfma_f32_16x16x32_bf16 v[120:123], v[164:167], v[188:191], v[120:123]
	v_mfma_f32_16x16x32_bf16 v[108:111], v[156:159], v[202:205], v[108:111]
	v_mfma_f32_16x16x32_bf16 v[104:107], v[164:167], v[202:205], v[104:107]
	v_mfma_f32_16x16x32_bf16 v[92:95], v[156:159], v[220:223], v[92:95]
	v_mfma_f32_16x16x32_bf16 v[88:91], v[164:167], v[220:223], v[88:91]
	v_mfma_f32_16x16x32_bf16 v[76:79], v[156:159], v[228:231], v[76:79]
	v_mfma_f32_16x16x32_bf16 v[72:75], v[164:167], v[228:231], v[72:75]
	v_mfma_f32_16x16x32_bf16 v[116:119], v[168:171], v[184:187], v[116:119]
	v_mfma_f32_16x16x32_bf16 v[112:115], v[176:179], v[184:187], v[112:115]
	v_mfma_f32_16x16x32_bf16 v[100:103], v[168:171], v[198:201], v[100:103]
	v_mfma_f32_16x16x32_bf16 v[96:99], v[176:179], v[198:201], v[96:99]
	v_mfma_f32_16x16x32_bf16 v[84:87], v[168:171], v[216:219], v[84:87]
	v_mfma_f32_16x16x32_bf16 v[80:83], v[176:179], v[216:219], v[80:83]
	v_mfma_f32_16x16x32_bf16 v[68:71], v[168:171], v[224:227], v[68:71]
	v_mfma_f32_16x16x32_bf16 v[64:67], v[176:179], v[224:227], v[64:67]
	v_mfma_f32_16x16x32_bf16 v[116:119], v[172:175], v[188:191], v[116:119]
	v_mfma_f32_16x16x32_bf16 v[112:115], v[180:183], v[188:191], v[112:115]
	v_mfma_f32_16x16x32_bf16 v[100:103], v[172:175], v[202:205], v[100:103]
	v_mfma_f32_16x16x32_bf16 v[96:99], v[180:183], v[202:205], v[96:99]
	v_mfma_f32_16x16x32_bf16 v[84:87], v[172:175], v[220:223], v[84:87]
	v_mfma_f32_16x16x32_bf16 v[80:83], v[180:183], v[220:223], v[80:83]
	v_mfma_f32_16x16x32_bf16 v[68:71], v[172:175], v[228:231], v[68:71]
	v_mfma_f32_16x16x32_bf16 v[64:67], v[180:183], v[228:231], v[64:67]
	s_barrier
	s_setprio 0
	s_add_i32 s51, s44, s33
	v_lshl_add_u64 v[192:193], s[28:29], 0, v[130:131]
	s_mov_b32 m0, s51
	ds_read_b128 v[184:187], v153 offset:16384
	ds_read_b128 v[188:191], v153 offset:17408
	ds_read_b128 v[198:201], v153 offset:18432
	ds_read_b128 v[202:205], v153 offset:19456
	ds_read_b128 v[216:219], v153 offset:20480
	ds_read_b128 v[220:223], v153 offset:21504
	ds_read_b128 v[224:227], v153 offset:22528
	ds_read_b128 v[228:231], v153 offset:23552
	global_load_lds_dwordx4 v[192:193], off
	s_add_i32 m0, s51, 0x2000
	s_add_u32 s52, s28, 0x100000
	v_lshl_add_u64 v[206:207], s[28:29], 0, v[134:135]
	s_addc_u32 s53, s29, 0
	s_add_i32 s51, s45, s33
	global_load_lds_dwordx4 v[206:207], off
	v_lshl_add_u64 v[210:211], s[52:53], 0, v[130:131]
	s_mov_b32 m0, s51
	v_lshl_add_u64 v[232:233], s[30:31], 0, v[132:133]
	global_load_lds_dwordx4 v[210:211], off
	v_lshl_add_u64 v[210:211], s[52:53], 0, v[134:135]
	s_add_i32 m0, s51, 0x2000
	s_nop 0
	global_load_lds_dwordx4 v[210:211], off
	v_lshl_add_u64 v[210:211], s[30:31], 0, v[128:129]
	s_mov_b32 m0, s34
	s_nop 0
	global_load_lds_dwordx4 v[210:211], off
	s_mov_b32 m0, s35
	s_nop 0
	global_load_lds_dwordx4 v[232:233], off
	s_waitcnt vmcnt(8)
	s_waitcnt lgkmcnt(0)
	s_setprio 1
	s_barrier
; #define PG8_STAGE(bufoff, gbase, voff) do { _Pragma("unroll") for (int _i = 0; _i < 2; ++_i) \
;         __builtin_amdgcn_global_load_lds((const unsigned*)((const char*)(gbase) + (voff)[_i]), (LAS unsigned*)(lds + (bufoff) + ldsw + _i * 8192), 16, 0, 0); } while (0)
; #define PG8_LDA(dst, b, h) do { _Pragma("unroll") for (int m = 0; m < 4; ++m) _Pragma("unroll") for (int k = 0; k < 2; ++k) dst[m][k] = *(const LAS bf16x8*)(lds + PG8_SA(b, h) + aoff + m * 2048 + k * 1024); } while (0)
; #define PG8_LDB(dst, b, h) do { _Pragma("unroll") for (int n = 0; n < 2; ++n) _Pragma("unroll") for (int k = 0; k < 2; ++k) dst[n][k] = *(const LAS bf16x8*)(lds + PG8_SB(b, h) + boff + n * 2048 + k * 1024); } while (0)
; #define PG8_MMA(ai, bj, At, Bt) do { __builtin_amdgcn_s_setprio(1); _Pragma("unroll") for (int m = 0; m < 4; ++m) _Pragma("unroll") for (int n = 0; n < 2; ++n) _Pragma("unroll") for (int k = 0; k < 2; ++k) \
;         acc[ai][bj][m][n] = __builtin_amdgcn_mfma_f32_16x16x32_bf16(Bt[n][k], At[m][k], acc[ai][bj][m][n], 0, 0, 0); __builtin_amdgcn_s_setprio(0); } while (0)
; #define PG8_WAIT_V(n) asm volatile("s_waitcnt vmcnt(" #n ")" ::: "memory")
; #define PG8_WAIT_L(n) asm volatile("s_waitcnt lgkmcnt(" #n ")" ::: "memory")
; #define PG8_BAR __builtin_amdgcn_s_barrier()
; #define PG8_SCHED __builtin_amdgcn_sched_barrier(0)
; template <class Epi, bool ALIGN_EPI, bool SP2 = PG8_SP2_DEFAULT>
; __device__ __forceinline__ void gemm_phase(LAS unsigned char* lds, const Gemm g, const StaticOrder& S, const Epi& E) {
;     ...
;             PG8_WAIT_V(8); PG8_WAIT_L(0); PG8_BAR; PG8_MMA(1, 0, At, B0); PG8_MMA(1, 1, At, B1); PG8_BAR; PG8_SCHED;
;             PG8_LDB(B0, 1, 0); PG8_LDB(B1, 1, 1); PG8_SCHED; PG8_LDA(At, 1, 0); PG8_STAGE(PG8_SA(0, 1), a2 + hstepA, voffA);
;             PG8_WAIT_V(8); PG8_WAIT_L(0); PG8_BAR; PG8_MMA(0, 0, At, B0); PG8_MMA(0, 1, At, B1); PG8_BAR; PG8_SCHED;
	v_mfma_f32_16x16x32_bf16 v[60:63], v[144:147], v[184:187], v[60:63]
	v_mfma_f32_16x16x32_bf16 v[56:59], v[160:163], v[184:187], v[56:59]
	v_mfma_f32_16x16x32_bf16 v[44:47], v[144:147], v[198:201], v[44:47]
	v_mfma_f32_16x16x32_bf16 v[40:43], v[160:163], v[198:201], v[40:43]
	v_mfma_f32_16x16x32_bf16 v[28:31], v[144:147], v[216:219], v[28:31]
	v_mfma_f32_16x16x32_bf16 v[24:27], v[160:163], v[216:219], v[24:27]
	v_mfma_f32_16x16x32_bf16 v[12:15], v[144:147], v[224:227], v[12:15]
	v_mfma_f32_16x16x32_bf16 v[8:11], v[160:163], v[224:227], v[8:11]
	v_mfma_f32_16x16x32_bf16 v[60:63], v[156:159], v[188:191], v[60:63]
	v_mfma_f32_16x16x32_bf16 v[56:59], v[164:167], v[188:191], v[56:59]
	v_mfma_f32_16x16x32_bf16 v[44:47], v[156:159], v[202:205], v[44:47]
	v_mfma_f32_16x16x32_bf16 v[40:43], v[164:167], v[202:205], v[40:43]
	v_mfma_f32_16x16x32_bf16 v[28:31], v[156:159], v[220:223], v[28:31]
	v_mfma_f32_16x16x32_bf16 v[24:27], v[164:167], v[220:223], v[24:27]
	v_mfma_f32_16x16x32_bf16 v[12:15], v[156:159], v[228:231], v[12:15]
	v_mfma_f32_16x16x32_bf16 v[8:11], v[164:167], v[228:231], v[8:11]
	v_mfma_f32_16x16x32_bf16 v[52:55], v[168:171], v[184:187], v[52:55]
	v_mfma_f32_16x16x32_bf16 v[48:51], v[176:179], v[184:187], v[48:51]
	v_mfma_f32_16x16x32_bf16 v[36:39], v[168:171], v[198:201], v[36:39]
	v_mfma_f32_16x16x32_bf16 v[32:35], v[176:179], v[198:201], v[32:35]
	v_mfma_f32_16x16x32_bf16 v[20:23], v[168:171], v[216:219], v[20:23]
	v_mfma_f32_16x16x32_bf16 v[16:19], v[176:179], v[216:219], v[16:19]
	v_mfma_f32_16x16x32_bf16 v[4:7], v[168:171], v[224:227], v[4:7]
	v_mfma_f32_16x16x32_bf16 v[0:3], v[176:179], v[224:227], v[0:3]
	v_mfma_f32_16x16x32_bf16 v[52:55], v[172:175], v[188:191], v[52:55]
	v_mfma_f32_16x16x32_bf16 v[48:51], v[180:183], v[188:191], v[48:51]
	v_mfma_f32_16x16x32_bf16 v[36:39], v[172:175], v[202:205], v[36:39]
	v_mfma_f32_16x16x32_bf16 v[32:35], v[180:183], v[202:205], v[32:35]
	v_mfma_f32_16x16x32_bf16 v[20:23], v[172:175], v[220:223], v[20:23]
	v_mfma_f32_16x16x32_bf16 v[16:19], v[180:183], v[220:223], v[16:19]
	v_mfma_f32_16x16x32_bf16 v[4:7], v[172:175], v[228:231], v[4:7]
	v_mfma_f32_16x16x32_bf16 v[0:3], v[180:183], v[228:231], v[0:3]
	s_barrier
	s_setprio 0
	s_add_i32 s51, 0, 0x18000
	v_add_u32_e32 v155, s51, v149
	s_add_i32 s52, 0, 0x1c000
	ds_read_b128 v[144:147], v155
	ds_read_b128 v[156:159], v155 offset:1024
	ds_read_b128 v[160:163], v155 offset:2048
	ds_read_b128 v[164:167], v155 offset:3072
	v_add_u32_e32 v155, s52, v149
	ds_read_b128 v[168:171], v155
	ds_read_b128 v[172:175], v155 offset:1024
	ds_read_b128 v[176:179], v155 offset:2048
	ds_read_b128 v[180:183], v155 offset:3072
	s_add_u32 s30, s30, 0x100000
	s_addc_u32 s31, s31, 0
	s_mov_b32 m0, s36
	v_lshl_add_u64 v[234:235], s[30:31], 0, v[128:129]
	ds_read_b128 v[184:187], v153 offset:32768
	ds_read_b128 v[188:191], v153 offset:33792
	ds_read_b128 v[198:201], v153 offset:34816
	ds_read_b128 v[202:205], v153 offset:35840
	ds_read_b128 v[216:219], v153 offset:36864
	ds_read_b128 v[220:223], v153 offset:37888
	ds_read_b128 v[224:227], v153 offset:38912
	ds_read_b128 v[228:231], v153 offset:39936
	global_load_lds_dwordx4 v[234:235], off
	v_lshl_add_u64 v[234:235], s[30:31], 0, v[132:133]
	s_mov_b32 m0, s37
	s_nop 0
	global_load_lds_dwordx4 v[234:235], off
	s_waitcnt vmcnt(8)
	s_waitcnt lgkmcnt(0)
	s_setprio 1
	s_barrier
	v_mfma_f32_16x16x32_bf16 v[124:127], v[144:147], v[184:187], v[124:127]
	v_mfma_f32_16x16x32_bf16 v[120:123], v[160:163], v[184:187], v[120:123]
	v_mfma_f32_16x16x32_bf16 v[108:111], v[144:147], v[198:201], v[108:111]
	v_mfma_f32_16x16x32_bf16 v[104:107], v[160:163], v[198:201], v[104:107]
	v_mfma_f32_16x16x32_bf16 v[92:95], v[144:147], v[216:219], v[92:95]
	v_mfma_f32_16x16x32_bf16 v[88:91], v[160:163], v[216:219], v[88:91]
	v_mfma_f32_16x16x32_bf16 v[76:79], v[144:147], v[224:227], v[76:79]
	v_mfma_f32_16x16x32_bf16 v[72:75], v[160:163], v[224:227], v[72:75]
	v_mfma_f32_16x16x32_bf16 v[124:127], v[156:159], v[188:191], v[124:127]
	v_mfma_f32_16x16x32_bf16 v[120:123], v[164:167], v[188:191], v[120:123]
	v_mfma_f32_16x16x32_bf16 v[108:111], v[156:159], v[202:205], v[108:111]
	v_mfma_f32_16x16x32_bf16 v[104:107], v[164:167], v[202:205], v[104:107]
	v_mfma_f32_16x16x32_bf16 v[92:95], v[156:159], v[220:223], v[92:95]
	v_mfma_f32_16x16x32_bf16 v[88:91], v[164:167], v[220:223], v[88:91]
	v_mfma_f32_16x16x32_bf16 v[76:79], v[156:159], v[228:231], v[76:79]
	v_mfma_f32_16x16x32_bf16 v[72:75], v[164:167], v[228:231], v[72:75]
	v_mfma_f32_16x16x32_bf16 v[116:119], v[168:171], v[184:187], v[116:119]
	v_mfma_f32_16x16x32_bf16 v[112:115], v[176:179], v[184:187], v[112:115]
	v_mfma_f32_16x16x32_bf16 v[100:103], v[168:171], v[198:201], v[100:103]
	v_mfma_f32_16x16x32_bf16 v[96:99], v[176:179], v[198:201], v[96:99]
	v_mfma_f32_16x16x32_bf16 v[84:87], v[168:171], v[216:219], v[84:87]
	v_mfma_f32_16x16x32_bf16 v[80:83], v[176:179], v[216:219], v[80:83]
	v_mfma_f32_16x16x32_bf16 v[68:71], v[168:171], v[224:227], v[68:71]
	v_mfma_f32_16x16x32_bf16 v[64:67], v[176:179], v[224:227], v[64:67]
	v_mfma_f32_16x16x32_bf16 v[116:119], v[172:175], v[188:191], v[116:119]
	v_mfma_f32_16x16x32_bf16 v[112:115], v[180:183], v[188:191], v[112:115]
	v_mfma_f32_16x16x32_bf16 v[100:103], v[172:175], v[202:205], v[100:103]
	v_mfma_f32_16x16x32_bf16 v[96:99], v[180:183], v[202:205], v[96:99]
	v_mfma_f32_16x16x32_bf16 v[84:87], v[172:175], v[220:223], v[84:87]
	v_mfma_f32_16x16x32_bf16 v[80:83], v[180:183], v[220:223], v[80:83]
	v_mfma_f32_16x16x32_bf16 v[68:71], v[172:175], v[228:231], v[68:71]
	v_mfma_f32_16x16x32_bf16 v[64:67], v[180:183], v[228:231], v[64:67]
	s_barrier
; #define PG8_STAGE(bufoff, gbase, voff) do { _Pragma("unroll") for (int _i = 0; _i < 2; ++_i) \
;         __builtin_amdgcn_global_load_lds((const unsigned*)((const char*)(gbase) + (voff)[_i]), (LAS unsigned*)(lds + (bufoff) + ldsw + _i * 8192), 16, 0, 0); } while (0)
; #define PG8_LDA(dst, b, h) do { _Pragma("unroll") for (int m = 0; m < 4; ++m) _Pragma("unroll") for (int k = 0; k < 2; ++k) dst[m][k] = *(const LAS bf16x8*)(lds + PG8_SA(b, h) + aoff + m * 2048 + k * 1024); } while (0)
; #define PG8_MMA(ai, bj, At, Bt) do { __builtin_amdgcn_s_setprio(1); _Pragma("unroll") for (int m = 0; m < 4; ++m) _Pragma("unroll") for (int n = 0; n < 2; ++n) _Pragma("unroll") for (int k = 0; k < 2; ++k) \
;         acc[ai][bj][m][n] = __builtin_amdgcn_mfma_f32_16x16x32_bf16(Bt[n][k], At[m][k], acc[ai][bj][m][n], 0, 0, 0); __builtin_amdgcn_s_setprio(0); } while (0)
; #define PG8_WAIT_V(n) asm volatile("s_waitcnt vmcnt(" #n ")" ::: "memory")
; #define PG8_WAIT_L(n) asm volatile("s_waitcnt lgkmcnt(" #n ")" ::: "memory")
; #define PG8_BAR __builtin_amdgcn_s_barrier()
; #define PG8_SCHED __builtin_amdgcn_sched_barrier(0)
; template <class Epi, bool ALIGN_EPI, bool SP2 = PG8_SP2_DEFAULT>
; __device__ __forceinline__ void gemm_phase(LAS unsigned char* lds, const Gemm g, const StaticOrder& S, const Epi& E) {
;     ...
;         for (int t = 0; t < nt; t += 2) {
;     ...
;             PG8_LDA(At, 1, 1); PG8_STAGE(PG8_SB(1, 0), b3, voffB); PG8_STAGE(PG8_SB(1, 1), b3 + hstepB, voffB); PG8_STAGE(PG8_SA(1, 0), a3, voffA);
;             PG8_WAIT_V(8); PG8_WAIT_L(0); PG8_BAR; PG8_MMA(1, 0, At, B0); PG8_MMA(1, 1, At, B1); PG8_BAR; PG8_SCHED;
;     ...
;         if constexpr (ALIGN_EPI) { if (wr == 0) PG8_BAR; }
	s_setprio 0
	s_add_i32 s30, s51, s33
	v_lshl_add_u64 v[192:193], v[192:193], 0, s[14:15]
	s_mov_b32 m0, s30
	ds_read_b128 v[184:187], v153 offset:49152
	ds_read_b128 v[188:191], v153 offset:50176
	ds_read_b128 v[198:201], v153 offset:51200
	ds_read_b128 v[202:205], v153 offset:52224
	ds_read_b128 v[216:219], v153 offset:53248
	ds_read_b128 v[220:223], v153 offset:54272
	ds_read_b128 v[224:227], v153 offset:55296
	ds_read_b128 v[228:231], v153 offset:56320
	global_load_lds_dwordx4 v[192:193], off
	s_add_i32 m0, s30, 0x2000
	s_add_u32 s28, s28, 0x100080
	v_lshl_add_u64 v[192:193], v[206:207], 0, s[14:15]
	s_addc_u32 s29, s29, 0
	s_add_i32 s30, s52, s33
	global_load_lds_dwordx4 v[192:193], off
	v_lshl_add_u64 v[192:193], s[28:29], 0, v[130:131]
	s_mov_b32 m0, s30
	s_nop 0
	global_load_lds_dwordx4 v[192:193], off
	v_lshl_add_u64 v[192:193], s[28:29], 0, v[134:135]
	s_add_i32 m0, s30, 0x2000
	s_nop 0
	global_load_lds_dwordx4 v[192:193], off
	v_lshl_add_u64 v[192:193], v[210:211], 0, s[14:15]
	s_mov_b32 m0, s39
	s_nop 0
	global_load_lds_dwordx4 v[192:193], off
	v_lshl_add_u64 v[192:193], v[232:233], 0, s[14:15]
	s_mov_b32 m0, s40
	s_nop 0
	global_load_lds_dwordx4 v[192:193], off
	s_waitcnt vmcnt(8)
	s_waitcnt lgkmcnt(0)
	s_setprio 1
	s_barrier
	v_mfma_f32_16x16x32_bf16 v[60:63], v[144:147], v[184:187], v[60:63]
	v_mfma_f32_16x16x32_bf16 v[56:59], v[160:163], v[184:187], v[56:59]
	v_mfma_f32_16x16x32_bf16 v[44:47], v[144:147], v[198:201], v[44:47]
	v_mfma_f32_16x16x32_bf16 v[40:43], v[160:163], v[198:201], v[40:43]
	v_mfma_f32_16x16x32_bf16 v[28:31], v[144:147], v[216:219], v[28:31]
	v_mfma_f32_16x16x32_bf16 v[24:27], v[160:163], v[216:219], v[24:27]
	v_mfma_f32_16x16x32_bf16 v[12:15], v[144:147], v[224:227], v[12:15]
	v_mfma_f32_16x16x32_bf16 v[8:11], v[160:163], v[224:227], v[8:11]
	v_mfma_f32_16x16x32_bf16 v[60:63], v[156:159], v[188:191], v[60:63]
	v_mfma_f32_16x16x32_bf16 v[56:59], v[164:167], v[188:191], v[56:59]
	v_mfma_f32_16x16x32_bf16 v[44:47], v[156:159], v[202:205], v[44:47]
	v_mfma_f32_16x16x32_bf16 v[40:43], v[164:167], v[202:205], v[40:43]
	v_mfma_f32_16x16x32_bf16 v[28:31], v[156:159], v[220:223], v[28:31]
	v_mfma_f32_16x16x32_bf16 v[24:27], v[164:167], v[220:223], v[24:27]
	v_mfma_f32_16x16x32_bf16 v[12:15], v[156:159], v[228:231], v[12:15]
	v_mfma_f32_16x16x32_bf16 v[8:11], v[164:167], v[228:231], v[8:11]
	v_mfma_f32_16x16x32_bf16 v[52:55], v[168:171], v[184:187], v[52:55]
	v_mfma_f32_16x16x32_bf16 v[48:51], v[176:179], v[184:187], v[48:51]
	v_mfma_f32_16x16x32_bf16 v[36:39], v[168:171], v[198:201], v[36:39]
	v_mfma_f32_16x16x32_bf16 v[32:35], v[176:179], v[198:201], v[32:35]
	v_mfma_f32_16x16x32_bf16 v[20:23], v[168:171], v[216:219], v[20:23]
	v_mfma_f32_16x16x32_bf16 v[16:19], v[176:179], v[216:219], v[16:19]
	v_mfma_f32_16x16x32_bf16 v[4:7], v[168:171], v[224:227], v[4:7]
	v_mfma_f32_16x16x32_bf16 v[0:3], v[176:179], v[224:227], v[0:3]
	v_mfma_f32_16x16x32_bf16 v[52:55], v[172:175], v[188:191], v[52:55]
	v_mfma_f32_16x16x32_bf16 v[48:51], v[180:183], v[188:191], v[48:51]
	v_mfma_f32_16x16x32_bf16 v[36:39], v[172:175], v[202:205], v[36:39]
	v_mfma_f32_16x16x32_bf16 v[32:35], v[180:183], v[202:205], v[32:35]
	v_mfma_f32_16x16x32_bf16 v[20:23], v[172:175], v[220:223], v[20:23]
	v_mfma_f32_16x16x32_bf16 v[16:19], v[180:183], v[220:223], v[16:19]
	v_mfma_f32_16x16x32_bf16 v[4:7], v[172:175], v[228:231], v[4:7]
	v_mfma_f32_16x16x32_bf16 v[0:3], v[180:183], v[228:231], v[0:3]
	s_barrier
	s_setprio 0
	s_add_i32 s50, s50, 2
	s_add_u32 s26, s26, 0x100
	s_addc_u32 s27, s27, 0
	s_add_u32 s48, s48, 0x100
	s_addc_u32 s49, s49, 0
	s_cmp_gt_u32 s50, 61
	s_cbranch_scc0 .LBB0_506
	s_and_b64 vcc, exec, s[16:17]
	s_cbranch_vccz .LBB0_509
	s_barrier

; #define PG8_STAGE(bufoff, gbase, voff) do { _Pragma("unroll") for (int _i = 0; _i < 2; ++_i) \
;         __builtin_amdgcn_global_load_lds((const unsigned*)((const char*)(gbase) + (voff)[_i]), (LAS unsigned*)(lds + (bufoff) + ldsw + _i * 8192), 16, 0, 0); } while (0)
; #define PG8_LDA(dst, b, h) do { _Pragma("unroll") for (int m = 0; m < 4; ++m) _Pragma("unroll") for (int k = 0; k < 2; ++k) dst[m][k] = *(const LAS bf16x8*)(lds + PG8_SA(b, h) + aoff + m * 2048 + k * 1024); } while (0)
; #define PG8_LDB(dst, b, h) do { _Pragma("unroll") for (int n = 0; n < 2; ++n) _Pragma("unroll") for (int k = 0; k < 2; ++k) dst[n][k] = *(const LAS bf16x8*)(lds + PG8_SB(b, h) + boff + n * 2048 + k * 1024); } while (0)
; #define PG8_MMA(ai, bj, At, Bt) do { __builtin_amdgcn_s_setprio(1); _Pragma("unroll") for (int m = 0; m < 4; ++m) _Pragma("unroll") for (int n = 0; n < 2; ++n) _Pragma("unroll") for (int k = 0; k < 2; ++k) \
;         acc[ai][bj][m][n] = __builtin_amdgcn_mfma_f32_16x16x32_bf16(Bt[n][k], At[m][k], acc[ai][bj][m][n], 0, 0, 0); __builtin_amdgcn_s_setprio(0); } while (0)
; #define PG8_WAIT_V(n) asm volatile("s_waitcnt vmcnt(" #n ")" ::: "memory")
; #define PG8_WAIT_L(n) asm volatile("s_waitcnt lgkmcnt(" #n ")" ::: "memory")
; #define PG8_BAR __builtin_amdgcn_s_barrier()
; #define PG8_SCHED __builtin_amdgcn_sched_barrier(0)
; template <class Epi, bool ALIGN_EPI, bool SP2 = PG8_SP2_DEFAULT>
; __device__ __forceinline__ void gemm_phase(LAS unsigned char* lds, const Gemm g, const StaticOrder& S, const Epi& E) {
;     ...
;             const bool last = (t == nt - 2);
;             const char* a1 = cA + (size_t)(t + 1) * kstep;
;             const char* a2 = last ? nA : cA + (size_t)(t + 2) * kstep; const char* b2 = last ? nB : cB + (size_t)(t + 2) * kstep;
;             const char* a3 = a2 + kstep; const char* b3 = b2 + kstep;
;             if constexpr (SP2) {
;             PG8_LDB(B0, 0, 0); PG8_LDB(B1, 0, 1); PG8_SCHED; PG8_LDA(At, 0, 0); PG8_STAGE(PG8_SA(1, 1), a1 + hstepA, voffA);
;             PG8_WAIT_V(8); PG8_WAIT_L(0); PG8_BAR; PG8_MMA(0, 0, At, B0); PG8_MMA(0, 1, At, B1); PG8_BAR; PG8_SCHED;
;             PG8_LDA(At, 0, 1); PG8_STAGE(PG8_SB(0, 0), b2, voffB); PG8_STAGE(PG8_SB(0, 1), b2 + hstepB, voffB); PG8_STAGE(PG8_SA(0, 0), a2, voffA);
.LBB0_598:
	ds_read_b128 v[146:149], v155
	ds_read_b128 v[160:163], v155 offset:1024
	ds_read_b128 v[164:167], v155 offset:2048
	ds_read_b128 v[168:171], v155 offset:3072
	ds_read_b128 v[172:175], v156
	ds_read_b128 v[176:179], v156 offset:1024
	ds_read_b128 v[180:183], v156 offset:2048
	ds_read_b128 v[184:187], v156 offset:3072
	s_add_u32 s24, s22, 0xfff00080
	s_addc_u32 s25, s23, -1
	s_cmp_eq_u32 s47, 60
	s_cselect_b32 s27, s3, s25
	s_cselect_b32 s26, s7, s24
	s_cselect_b32 s25, s9, s45
	s_cselect_b32 s24, s17, s44
	v_lshl_add_u64 v[192:193], s[22:23], 0, v[138:139]
	s_add_i32 m0, s30, 0xc000
	ds_read_b128 v[188:191], v157
	ds_read_b128 v[198:201], v157 offset:1024
	ds_read_b128 v[202:205], v157 offset:2048
	ds_read_b128 v[214:217], v157 offset:3072
	ds_read_b128 v[218:221], v157 offset:4096
	ds_read_b128 v[222:225], v157 offset:5120
	ds_read_b128 v[226:229], v157 offset:6144
	ds_read_b128 v[230:233], v157 offset:7168
	global_load_lds_dwordx4 v[192:193], off
	v_lshl_add_u64 v[192:193], s[22:23], 0, v[140:141]
	s_add_i32 m0, s30, 0xe000
	s_nop 0
	global_load_lds_dwordx4 v[192:193], off
	s_waitcnt vmcnt(8)
	s_waitcnt lgkmcnt(0)
	s_setprio 1
	s_barrier
	v_mfma_f32_16x16x32_bf16 v[124:127], v[146:149], v[188:191], v[124:127]
	v_mfma_f32_16x16x32_bf16 v[120:123], v[164:167], v[188:191], v[120:123]
	v_mfma_f32_16x16x32_bf16 v[108:111], v[146:149], v[202:205], v[108:111]
	v_mfma_f32_16x16x32_bf16 v[104:107], v[164:167], v[202:205], v[104:107]
	v_mfma_f32_16x16x32_bf16 v[92:95], v[146:149], v[218:221], v[92:95]
	v_mfma_f32_16x16x32_bf16 v[88:91], v[164:167], v[218:221], v[88:91]
	v_mfma_f32_16x16x32_bf16 v[76:79], v[146:149], v[226:229], v[76:79]
	v_mfma_f32_16x16x32_bf16 v[72:75], v[164:167], v[226:229], v[72:75]
	v_mfma_f32_16x16x32_bf16 v[124:127], v[160:163], v[198:201], v[124:127]
	v_mfma_f32_16x16x32_bf16 v[120:123], v[168:171], v[198:201], v[120:123]
	v_mfma_f32_16x16x32_bf16 v[108:111], v[160:163], v[214:217], v[108:111]
	v_mfma_f32_16x16x32_bf16 v[104:107], v[168:171], v[214:217], v[104:107]
	v_mfma_f32_16x16x32_bf16 v[92:95], v[160:163], v[222:225], v[92:95]
	v_mfma_f32_16x16x32_bf16 v[88:91], v[168:171], v[222:225], v[88:91]
	v_mfma_f32_16x16x32_bf16 v[76:79], v[160:163], v[230:233], v[76:79]
	v_mfma_f32_16x16x32_bf16 v[72:75], v[168:171], v[230:233], v[72:75]
	v_mfma_f32_16x16x32_bf16 v[116:119], v[172:175], v[188:191], v[116:119]
	v_mfma_f32_16x16x32_bf16 v[112:115], v[180:183], v[188:191], v[112:115]
	v_mfma_f32_16x16x32_bf16 v[100:103], v[172:175], v[202:205], v[100:103]
	v_mfma_f32_16x16x32_bf16 v[96:99], v[180:183], v[202:205], v[96:99]
	v_mfma_f32_16x16x32_bf16 v[84:87], v[172:175], v[218:221], v[84:87]
	v_mfma_f32_16x16x32_bf16 v[80:83], v[180:183], v[218:221], v[80:83]
	v_mfma_f32_16x16x32_bf16 v[68:71], v[172:175], v[226:229], v[68:71]
	v_mfma_f32_16x16x32_bf16 v[64:67], v[180:183], v[226:229], v[64:67]
	v_mfma_f32_16x16x32_bf16 v[116:119], v[176:179], v[198:201], v[116:119]
	v_mfma_f32_16x16x32_bf16 v[112:115], v[184:187], v[198:201], v[112:115]
	v_mfma_f32_16x16x32_bf16 v[100:103], v[176:179], v[214:217], v[100:103]
	v_mfma_f32_16x16x32_bf16 v[96:99], v[184:187], v[214:217], v[96:99]
	v_mfma_f32_16x16x32_bf16 v[84:87], v[176:179], v[222:225], v[84:87]
	v_mfma_f32_16x16x32_bf16 v[80:83], v[184:187], v[222:225], v[80:83]
	v_mfma_f32_16x16x32_bf16 v[68:71], v[176:179], v[230:233], v[68:71]
	v_mfma_f32_16x16x32_bf16 v[64:67], v[184:187], v[230:233], v[64:67]
	s_barrier
	s_setprio 0
	s_add_i32 s48, s41, s29
	v_lshl_add_u64 v[192:193], s[24:25], 0, v[130:131]
	s_mov_b32 m0, s48
	ds_read_b128 v[188:191], v157 offset:16384
	ds_read_b128 v[198:201], v157 offset:17408
	ds_read_b128 v[202:205], v157 offset:18432
	ds_read_b128 v[214:217], v157 offset:19456
	ds_read_b128 v[218:221], v157 offset:20480
	ds_read_b128 v[222:225], v157 offset:21504
	ds_read_b128 v[226:229], v157 offset:22528
	ds_read_b128 v[230:233], v157 offset:23552
	global_load_lds_dwordx4 v[192:193], off
	s_add_i32 m0, s48, 0x2000
	s_add_u32 s48, s24, 0x100000
	v_lshl_add_u64 v[206:207], s[24:25], 0, v[134:135]
	s_addc_u32 s49, s25, 0
	s_add_i32 s50, s42, s29
	global_load_lds_dwordx4 v[206:207], off
	v_lshl_add_u64 v[210:211], s[48:49], 0, v[130:131]
	s_mov_b32 m0, s50
	v_lshl_add_u64 v[234:235], s[26:27], 0, v[132:133]
	global_load_lds_dwordx4 v[210:211], off
	v_lshl_add_u64 v[210:211], s[48:49], 0, v[134:135]
	s_add_i32 m0, s50, 0x2000
	s_nop 0
	global_load_lds_dwordx4 v[210:211], off
	v_lshl_add_u64 v[210:211], s[26:27], 0, v[128:129]
	s_mov_b32 m0, s30
	s_nop 0
	global_load_lds_dwordx4 v[210:211], off
	s_mov_b32 m0, s31
	s_nop 0
	global_load_lds_dwordx4 v[234:235], off
	s_waitcnt vmcnt(8)
	s_waitcnt lgkmcnt(0)
	s_setprio 1
	s_barrier
; #define PG8_STAGE(bufoff, gbase, voff) do { _Pragma("unroll") for (int _i = 0; _i < 2; ++_i) \
;         __builtin_amdgcn_global_load_lds((const unsigned*)((const char*)(gbase) + (voff)[_i]), (LAS unsigned*)(lds + (bufoff) + ldsw + _i * 8192), 16, 0, 0); } while (0)
; #define PG8_LDA(dst, b, h) do { _Pragma("unroll") for (int m = 0; m < 4; ++m) _Pragma("unroll") for (int k = 0; k < 2; ++k) dst[m][k] = *(const LAS bf16x8*)(lds + PG8_SA(b, h) + aoff + m * 2048 + k * 1024); } while (0)
; #define PG8_LDB(dst, b, h) do { _Pragma("unroll") for (int n = 0; n < 2; ++n) _Pragma("unroll") for (int k = 0; k < 2; ++k) dst[n][k] = *(const LAS bf16x8*)(lds + PG8_SB(b, h) + boff + n * 2048 + k * 1024); } while (0)
; #define PG8_MMA(ai, bj, At, Bt) do { __builtin_amdgcn_s_setprio(1); _Pragma("unroll") for (int m = 0; m < 4; ++m) _Pragma("unroll") for (int n = 0; n < 2; ++n) _Pragma("unroll") for (int k = 0; k < 2; ++k) \
;         acc[ai][bj][m][n] = __builtin_amdgcn_mfma_f32_16x16x32_bf16(Bt[n][k], At[m][k], acc[ai][bj][m][n], 0, 0, 0); __builtin_amdgcn_s_setprio(0); } while (0)
; #define PG8_WAIT_V(n) asm volatile("s_waitcnt vmcnt(" #n ")" ::: "memory")
; #define PG8_WAIT_L(n) asm volatile("s_waitcnt lgkmcnt(" #n ")" ::: "memory")
; #define PG8_BAR __builtin_amdgcn_s_barrier()
; #define PG8_SCHED __builtin_amdgcn_sched_barrier(0)
; template <class Epi, bool ALIGN_EPI, bool SP2 = PG8_SP2_DEFAULT>
; __device__ __forceinline__ void gemm_phase(LAS unsigned char* lds, const Gemm g, const StaticOrder& S, const Epi& E) {
;     ...
;             PG8_WAIT_V(8); PG8_WAIT_L(0); PG8_BAR; PG8_MMA(1, 0, At, B0); PG8_MMA(1, 1, At, B1); PG8_BAR; PG8_SCHED;
;             PG8_LDB(B0, 1, 0); PG8_LDB(B1, 1, 1); PG8_SCHED; PG8_LDA(At, 1, 0); PG8_STAGE(PG8_SA(0, 1), a2 + hstepA, voffA);
;             PG8_WAIT_V(8); PG8_WAIT_L(0); PG8_BAR; PG8_MMA(0, 0, At, B0); PG8_MMA(0, 1, At, B1); PG8_BAR; PG8_SCHED;
	v_mfma_f32_16x16x32_bf16 v[60:63], v[146:149], v[188:191], v[60:63]
	v_mfma_f32_16x16x32_bf16 v[56:59], v[164:167], v[188:191], v[56:59]
	v_mfma_f32_16x16x32_bf16 v[44:47], v[146:149], v[202:205], v[44:47]
	v_mfma_f32_16x16x32_bf16 v[40:43], v[164:167], v[202:205], v[40:43]
	v_mfma_f32_16x16x32_bf16 v[28:31], v[146:149], v[218:221], v[28:31]
	v_mfma_f32_16x16x32_bf16 v[24:27], v[164:167], v[218:221], v[24:27]
	v_mfma_f32_16x16x32_bf16 v[12:15], v[146:149], v[226:229], v[12:15]
	v_mfma_f32_16x16x32_bf16 v[8:11], v[164:167], v[226:229], v[8:11]
	v_mfma_f32_16x16x32_bf16 v[60:63], v[160:163], v[198:201], v[60:63]
	v_mfma_f32_16x16x32_bf16 v[56:59], v[168:171], v[198:201], v[56:59]
	v_mfma_f32_16x16x32_bf16 v[44:47], v[160:163], v[214:217], v[44:47]
	v_mfma_f32_16x16x32_bf16 v[40:43], v[168:171], v[214:217], v[40:43]
	v_mfma_f32_16x16x32_bf16 v[28:31], v[160:163], v[222:225], v[28:31]
	v_mfma_f32_16x16x32_bf16 v[24:27], v[168:171], v[222:225], v[24:27]
	v_mfma_f32_16x16x32_bf16 v[12:15], v[160:163], v[230:233], v[12:15]
	v_mfma_f32_16x16x32_bf16 v[8:11], v[168:171], v[230:233], v[8:11]
	v_mfma_f32_16x16x32_bf16 v[52:55], v[172:175], v[188:191], v[52:55]
	v_mfma_f32_16x16x32_bf16 v[48:51], v[180:183], v[188:191], v[48:51]
	v_mfma_f32_16x16x32_bf16 v[36:39], v[172:175], v[202:205], v[36:39]
	v_mfma_f32_16x16x32_bf16 v[32:35], v[180:183], v[202:205], v[32:35]
	v_mfma_f32_16x16x32_bf16 v[20:23], v[172:175], v[218:221], v[20:23]
	v_mfma_f32_16x16x32_bf16 v[16:19], v[180:183], v[218:221], v[16:19]
	v_mfma_f32_16x16x32_bf16 v[4:7], v[172:175], v[226:229], v[4:7]
	v_mfma_f32_16x16x32_bf16 v[0:3], v[180:183], v[226:229], v[0:3]
	v_mfma_f32_16x16x32_bf16 v[52:55], v[176:179], v[198:201], v[52:55]
	v_mfma_f32_16x16x32_bf16 v[48:51], v[184:187], v[198:201], v[48:51]
	v_mfma_f32_16x16x32_bf16 v[36:39], v[176:179], v[214:217], v[36:39]
	v_mfma_f32_16x16x32_bf16 v[32:35], v[184:187], v[214:217], v[32:35]
	v_mfma_f32_16x16x32_bf16 v[20:23], v[176:179], v[222:225], v[20:23]
	v_mfma_f32_16x16x32_bf16 v[16:19], v[184:187], v[222:225], v[16:19]
	v_mfma_f32_16x16x32_bf16 v[4:7], v[176:179], v[230:233], v[4:7]
	v_mfma_f32_16x16x32_bf16 v[0:3], v[184:187], v[230:233], v[0:3]
	s_barrier
	s_setprio 0
	s_add_i32 s48, 0, 0x18000
	v_add_u32_e32 v150, s48, v152
	s_add_i32 s49, 0, 0x1c000
	ds_read_b128 v[146:149], v150
	ds_read_b128 v[160:163], v150 offset:1024
	ds_read_b128 v[164:167], v150 offset:2048
	ds_read_b128 v[168:171], v150 offset:3072
	v_add_u32_e32 v150, s49, v152
	ds_read_b128 v[172:175], v150
	ds_read_b128 v[176:179], v150 offset:1024
	ds_read_b128 v[180:183], v150 offset:2048
	ds_read_b128 v[184:187], v150 offset:3072
	s_add_u32 s26, s26, 0x100000
	s_addc_u32 s27, s27, 0
	s_mov_b32 m0, s33
	v_lshl_add_u64 v[236:237], s[26:27], 0, v[128:129]
	ds_read_b128 v[188:191], v157 offset:32768
	ds_read_b128 v[198:201], v157 offset:33792
	ds_read_b128 v[202:205], v157 offset:34816
	ds_read_b128 v[214:217], v157 offset:35840
	ds_read_b128 v[218:221], v157 offset:36864
	ds_read_b128 v[222:225], v157 offset:37888
	ds_read_b128 v[226:229], v157 offset:38912
	ds_read_b128 v[230:233], v157 offset:39936
	global_load_lds_dwordx4 v[236:237], off
	v_lshl_add_u64 v[236:237], s[26:27], 0, v[132:133]
	s_mov_b32 m0, s34
	s_nop 0
	global_load_lds_dwordx4 v[236:237], off
	s_waitcnt vmcnt(8)
	s_waitcnt lgkmcnt(0)
	s_setprio 1
	s_barrier
	v_mfma_f32_16x16x32_bf16 v[124:127], v[146:149], v[188:191], v[124:127]
	v_mfma_f32_16x16x32_bf16 v[120:123], v[164:167], v[188:191], v[120:123]
	v_mfma_f32_16x16x32_bf16 v[108:111], v[146:149], v[202:205], v[108:111]
	v_mfma_f32_16x16x32_bf16 v[104:107], v[164:167], v[202:205], v[104:107]
	v_mfma_f32_16x16x32_bf16 v[92:95], v[146:149], v[218:221], v[92:95]
	v_mfma_f32_16x16x32_bf16 v[88:91], v[164:167], v[218:221], v[88:91]
	v_mfma_f32_16x16x32_bf16 v[76:79], v[146:149], v[226:229], v[76:79]
	v_mfma_f32_16x16x32_bf16 v[72:75], v[164:167], v[226:229], v[72:75]
	v_mfma_f32_16x16x32_bf16 v[124:127], v[160:163], v[198:201], v[124:127]
	v_mfma_f32_16x16x32_bf16 v[120:123], v[168:171], v[198:201], v[120:123]
	v_mfma_f32_16x16x32_bf16 v[108:111], v[160:163], v[214:217], v[108:111]
	v_mfma_f32_16x16x32_bf16 v[104:107], v[168:171], v[214:217], v[104:107]
	v_mfma_f32_16x16x32_bf16 v[92:95], v[160:163], v[222:225], v[92:95]
	v_mfma_f32_16x16x32_bf16 v[88:91], v[168:171], v[222:225], v[88:91]
	v_mfma_f32_16x16x32_bf16 v[76:79], v[160:163], v[230:233], v[76:79]
	v_mfma_f32_16x16x32_bf16 v[72:75], v[168:171], v[230:233], v[72:75]
	v_mfma_f32_16x16x32_bf16 v[116:119], v[172:175], v[188:191], v[116:119]
	v_mfma_f32_16x16x32_bf16 v[112:115], v[180:183], v[188:191], v[112:115]
	v_mfma_f32_16x16x32_bf16 v[100:103], v[172:175], v[202:205], v[100:103]
	v_mfma_f32_16x16x32_bf16 v[96:99], v[180:183], v[202:205], v[96:99]
	v_mfma_f32_16x16x32_bf16 v[84:87], v[172:175], v[218:221], v[84:87]
	v_mfma_f32_16x16x32_bf16 v[80:83], v[180:183], v[218:221], v[80:83]
	v_mfma_f32_16x16x32_bf16 v[68:71], v[172:175], v[226:229], v[68:71]
	v_mfma_f32_16x16x32_bf16 v[64:67], v[180:183], v[226:229], v[64:67]
	v_mfma_f32_16x16x32_bf16 v[116:119], v[176:179], v[198:201], v[116:119]
	v_mfma_f32_16x16x32_bf16 v[112:115], v[184:187], v[198:201], v[112:115]
	v_mfma_f32_16x16x32_bf16 v[100:103], v[176:179], v[214:217], v[100:103]
	v_mfma_f32_16x16x32_bf16 v[96:99], v[184:187], v[214:217], v[96:99]
	v_mfma_f32_16x16x32_bf16 v[84:87], v[176:179], v[222:225], v[84:87]
	v_mfma_f32_16x16x32_bf16 v[80:83], v[184:187], v[222:225], v[80:83]
	v_mfma_f32_16x16x32_bf16 v[68:71], v[176:179], v[230:233], v[68:71]
	v_mfma_f32_16x16x32_bf16 v[64:67], v[184:187], v[230:233], v[64:67]
	s_barrier
; #define PG8_STAGE(bufoff, gbase, voff) do { _Pragma("unroll") for (int _i = 0; _i < 2; ++_i) \
;         __builtin_amdgcn_global_load_lds((const unsigned*)((const char*)(gbase) + (voff)[_i]), (LAS unsigned*)(lds + (bufoff) + ldsw + _i * 8192), 16, 0, 0); } while (0)
; #define PG8_LDA(dst, b, h) do { _Pragma("unroll") for (int m = 0; m < 4; ++m) _Pragma("unroll") for (int k = 0; k < 2; ++k) dst[m][k] = *(const LAS bf16x8*)(lds + PG8_SA(b, h) + aoff + m * 2048 + k * 1024); } while (0)
; #define PG8_MMA(ai, bj, At, Bt) do { __builtin_amdgcn_s_setprio(1); _Pragma("unroll") for (int m = 0; m < 4; ++m) _Pragma("unroll") for (int n = 0; n < 2; ++n) _Pragma("unroll") for (int k = 0; k < 2; ++k) \
;         acc[ai][bj][m][n] = __builtin_amdgcn_mfma_f32_16x16x32_bf16(Bt[n][k], At[m][k], acc[ai][bj][m][n], 0, 0, 0); __builtin_amdgcn_s_setprio(0); } while (0)
; #define PG8_WAIT_V(n) asm volatile("s_waitcnt vmcnt(" #n ")" ::: "memory")
; #define PG8_WAIT_L(n) asm volatile("s_waitcnt lgkmcnt(" #n ")" ::: "memory")
; #define PG8_BAR __builtin_amdgcn_s_barrier()
; #define PG8_SCHED __builtin_amdgcn_sched_barrier(0)
; template <class Epi, bool ALIGN_EPI, bool SP2 = PG8_SP2_DEFAULT>
; __device__ __forceinline__ void gemm_phase(LAS unsigned char* lds, const Gemm g, const StaticOrder& S, const Epi& E) {
;     ...
;         for (int t = 0; t < nt; t += 2) {
;     ...
;             PG8_LDA(At, 1, 1); PG8_STAGE(PG8_SB(1, 0), b3, voffB); PG8_STAGE(PG8_SB(1, 1), b3 + hstepB, voffB); PG8_STAGE(PG8_SA(1, 0), a3, voffA);
;             PG8_WAIT_V(8); PG8_WAIT_L(0); PG8_BAR; PG8_MMA(1, 0, At, B0); PG8_MMA(1, 1, At, B1); PG8_BAR; PG8_SCHED;
;     ...
;         if constexpr (ALIGN_EPI) { if (wr == 0) PG8_BAR; }
	s_setprio 0
	s_add_i32 s26, s48, s29
	v_lshl_add_u64 v[192:193], v[192:193], 0, s[12:13]
	s_mov_b32 m0, s26
	ds_read_b128 v[188:191], v157 offset:49152
	ds_read_b128 v[198:201], v157 offset:50176
	ds_read_b128 v[202:205], v157 offset:51200
	ds_read_b128 v[214:217], v157 offset:52224
	ds_read_b128 v[218:221], v157 offset:53248
	ds_read_b128 v[222:225], v157 offset:54272
	ds_read_b128 v[226:229], v157 offset:55296
	ds_read_b128 v[230:233], v157 offset:56320
	global_load_lds_dwordx4 v[192:193], off
	s_add_i32 m0, s26, 0x2000
	s_add_u32 s24, s24, 0x100080
	v_lshl_add_u64 v[192:193], v[206:207], 0, s[12:13]
	s_addc_u32 s25, s25, 0
	s_add_i32 s26, s49, s29
	global_load_lds_dwordx4 v[192:193], off
	v_lshl_add_u64 v[192:193], s[24:25], 0, v[130:131]
	s_mov_b32 m0, s26
	s_nop 0
	global_load_lds_dwordx4 v[192:193], off
	v_lshl_add_u64 v[192:193], s[24:25], 0, v[134:135]
	s_add_i32 m0, s26, 0x2000
	s_nop 0
	global_load_lds_dwordx4 v[192:193], off
	v_lshl_add_u64 v[192:193], v[210:211], 0, s[12:13]
	s_mov_b32 m0, s36
	s_nop 0
	global_load_lds_dwordx4 v[192:193], off
	v_lshl_add_u64 v[192:193], v[234:235], 0, s[12:13]
	s_mov_b32 m0, s37
	s_nop 0
	global_load_lds_dwordx4 v[192:193], off
	s_waitcnt vmcnt(8)
	s_waitcnt lgkmcnt(0)
	s_setprio 1
	s_barrier
	v_mfma_f32_16x16x32_bf16 v[60:63], v[146:149], v[188:191], v[60:63]
	v_mfma_f32_16x16x32_bf16 v[56:59], v[164:167], v[188:191], v[56:59]
	v_mfma_f32_16x16x32_bf16 v[44:47], v[146:149], v[202:205], v[44:47]
	v_mfma_f32_16x16x32_bf16 v[40:43], v[164:167], v[202:205], v[40:43]
	v_mfma_f32_16x16x32_bf16 v[28:31], v[146:149], v[218:221], v[28:31]
	v_mfma_f32_16x16x32_bf16 v[24:27], v[164:167], v[218:221], v[24:27]
	v_mfma_f32_16x16x32_bf16 v[12:15], v[146:149], v[226:229], v[12:15]
	v_mfma_f32_16x16x32_bf16 v[8:11], v[164:167], v[226:229], v[8:11]
	v_mfma_f32_16x16x32_bf16 v[60:63], v[160:163], v[198:201], v[60:63]
	v_mfma_f32_16x16x32_bf16 v[56:59], v[168:171], v[198:201], v[56:59]
	v_mfma_f32_16x16x32_bf16 v[44:47], v[160:163], v[214:217], v[44:47]
	v_mfma_f32_16x16x32_bf16 v[40:43], v[168:171], v[214:217], v[40:43]
	v_mfma_f32_16x16x32_bf16 v[28:31], v[160:163], v[222:225], v[28:31]
	v_mfma_f32_16x16x32_bf16 v[24:27], v[168:171], v[222:225], v[24:27]
	v_mfma_f32_16x16x32_bf16 v[12:15], v[160:163], v[230:233], v[12:15]
	v_mfma_f32_16x16x32_bf16 v[8:11], v[168:171], v[230:233], v[8:11]
	v_mfma_f32_16x16x32_bf16 v[52:55], v[172:175], v[188:191], v[52:55]
	v_mfma_f32_16x16x32_bf16 v[48:51], v[180:183], v[188:191], v[48:51]
	v_mfma_f32_16x16x32_bf16 v[36:39], v[172:175], v[202:205], v[36:39]
	v_mfma_f32_16x16x32_bf16 v[32:35], v[180:183], v[202:205], v[32:35]
	v_mfma_f32_16x16x32_bf16 v[20:23], v[172:175], v[218:221], v[20:23]
	v_mfma_f32_16x16x32_bf16 v[16:19], v[180:183], v[218:221], v[16:19]
	v_mfma_f32_16x16x32_bf16 v[4:7], v[172:175], v[226:229], v[4:7]
	v_mfma_f32_16x16x32_bf16 v[0:3], v[180:183], v[226:229], v[0:3]
	v_mfma_f32_16x16x32_bf16 v[52:55], v[176:179], v[198:201], v[52:55]
	v_mfma_f32_16x16x32_bf16 v[48:51], v[184:187], v[198:201], v[48:51]
	v_mfma_f32_16x16x32_bf16 v[36:39], v[176:179], v[214:217], v[36:39]
	v_mfma_f32_16x16x32_bf16 v[32:35], v[184:187], v[214:217], v[32:35]
	v_mfma_f32_16x16x32_bf16 v[20:23], v[176:179], v[222:225], v[20:23]
	v_mfma_f32_16x16x32_bf16 v[16:19], v[184:187], v[222:225], v[16:19]
	v_mfma_f32_16x16x32_bf16 v[4:7], v[176:179], v[230:233], v[4:7]
	v_mfma_f32_16x16x32_bf16 v[0:3], v[184:187], v[230:233], v[0:3]
	s_barrier
	s_setprio 0
	s_add_i32 s47, s47, 2
	s_add_u32 s22, s22, 0x100
	s_addc_u32 s23, s23, 0
	s_add_u32 s44, s44, 0x100
	s_addc_u32 s45, s45, 0
	s_cmp_gt_u32 s47, 61
	s_cbranch_scc0 .LBB0_598
	s_and_b64 vcc, exec, s[14:15]
	s_cbranch_vccz .LBB0_601
	s_barrier

; #define PG8_STAGE(bufoff, gbase, voff) do { _Pragma("unroll") for (int _i = 0; _i < 2; ++_i) \
;         __builtin_amdgcn_global_load_lds((const unsigned*)((const char*)(gbase) + (voff)[_i]), (LAS unsigned*)(lds + (bufoff) + ldsw + _i * 8192), 16, 0, 0); } while (0)
; #define PG8_LDA(dst, b, h) do { _Pragma("unroll") for (int m = 0; m < 4; ++m) _Pragma("unroll") for (int k = 0; k < 2; ++k) dst[m][k] = *(const LAS bf16x8*)(lds + PG8_SA(b, h) + aoff + m * 2048 + k * 1024); } while (0)
; #define PG8_LDB(dst, b, h) do { _Pragma("unroll") for (int n = 0; n < 2; ++n) _Pragma("unroll") for (int k = 0; k < 2; ++k) dst[n][k] = *(const LAS bf16x8*)(lds + PG8_SB(b, h) + boff + n * 2048 + k * 1024); } while (0)
; #define PG8_MMA(ai, bj, At, Bt) do { __builtin_amdgcn_s_setprio(1); _Pragma("unroll") for (int m = 0; m < 4; ++m) _Pragma("unroll") for (int n = 0; n < 2; ++n) _Pragma("unroll") for (int k = 0; k < 2; ++k) \
;         acc[ai][bj][m][n] = __builtin_amdgcn_mfma_f32_16x16x32_bf16(Bt[n][k], At[m][k], acc[ai][bj][m][n], 0, 0, 0); __builtin_amdgcn_s_setprio(0); } while (0)
; #define PG8_WAIT_V(n) asm volatile("s_waitcnt vmcnt(" #n ")" ::: "memory")
; #define PG8_WAIT_L(n) asm volatile("s_waitcnt lgkmcnt(" #n ")" ::: "memory")
; #define PG8_BAR __builtin_amdgcn_s_barrier()
; #define PG8_SCHED __builtin_amdgcn_sched_barrier(0)
; template <class Epi, bool ALIGN_EPI, bool SP2 = PG8_SP2_DEFAULT>
; __device__ __forceinline__ void gemm_phase(LAS unsigned char* lds, const Gemm g, const StaticOrder& S, const Epi& E) {
;     ...
;             const bool last = (t == nt - 2);
;             const char* a1 = cA + (size_t)(t + 1) * kstep;
;             const char* a2 = last ? nA : cA + (size_t)(t + 2) * kstep; const char* b2 = last ? nB : cB + (size_t)(t + 2) * kstep;
;             const char* a3 = a2 + kstep; const char* b3 = b2 + kstep;
;             if constexpr (SP2) {
;             PG8_LDB(B0, 0, 0); PG8_LDB(B1, 0, 1); PG8_SCHED; PG8_LDA(At, 0, 0); PG8_STAGE(PG8_SA(1, 1), a1 + hstepA, voffA);
;             PG8_WAIT_V(8); PG8_WAIT_L(0); PG8_BAR; PG8_MMA(0, 0, At, B0); PG8_MMA(0, 1, At, B1); PG8_BAR; PG8_SCHED;
;             PG8_LDA(At, 0, 1); PG8_STAGE(PG8_SB(0, 0), b2, voffB); PG8_STAGE(PG8_SB(0, 1), b2 + hstepB, voffB); PG8_STAGE(PG8_SA(0, 0), a2, voffA);
.LBB0_804:
	ds_read_b128 v[144:147], v153
	ds_read_b128 v[156:159], v153 offset:1024
	ds_read_b128 v[160:163], v153 offset:2048
	ds_read_b128 v[164:167], v153 offset:3072
	ds_read_b128 v[168:171], v154
	ds_read_b128 v[172:175], v154 offset:1024
	ds_read_b128 v[176:179], v154 offset:2048
	ds_read_b128 v[180:183], v154 offset:3072
	s_add_u32 s22, s20, 0x100
	s_addc_u32 s23, s21, 0
	s_cmpk_eq_i32 s49, 0xa8
	s_cselect_b32 s27, s5, s23
	s_cselect_b32 s26, s4, s22
	s_cselect_b32 s25, s19, s48
	s_cselect_b32 s24, s18, s47
	v_lshl_add_u64 v[148:149], s[20:21], 0, v[136:137]
	s_add_i32 m0, s31, 0xc000
	ds_read_b128 v[184:187], v155
	ds_read_b128 v[188:191], v155 offset:1024
	ds_read_b128 v[192:195], v155 offset:2048
	ds_read_b128 v[196:199], v155 offset:3072
	ds_read_b128 v[200:203], v155 offset:4096
	ds_read_b128 v[204:207], v155 offset:5120
	ds_read_b128 v[208:211], v155 offset:6144
	ds_read_b128 v[212:215], v155 offset:7168
	global_load_lds_dwordx4 v[148:149], off
	v_lshl_add_u64 v[148:149], s[20:21], 0, v[138:139]
	s_add_i32 m0, s31, 0xe000
	s_nop 0
	global_load_lds_dwordx4 v[148:149], off
	s_waitcnt vmcnt(8)
	s_waitcnt lgkmcnt(0)
	s_setprio 1
	s_barrier
	v_mfma_f32_16x16x32_bf16 v[124:127], v[144:147], v[184:187], v[124:127]
	v_mfma_f32_16x16x32_bf16 v[120:123], v[160:163], v[184:187], v[120:123]
	v_mfma_f32_16x16x32_bf16 v[108:111], v[144:147], v[192:195], v[108:111]
	v_mfma_f32_16x16x32_bf16 v[104:107], v[160:163], v[192:195], v[104:107]
	v_mfma_f32_16x16x32_bf16 v[92:95], v[144:147], v[200:203], v[92:95]
	v_mfma_f32_16x16x32_bf16 v[88:91], v[160:163], v[200:203], v[88:91]
	v_mfma_f32_16x16x32_bf16 v[76:79], v[144:147], v[208:211], v[76:79]
	v_mfma_f32_16x16x32_bf16 v[72:75], v[160:163], v[208:211], v[72:75]
	v_mfma_f32_16x16x32_bf16 v[124:127], v[156:159], v[188:191], v[124:127]
	v_mfma_f32_16x16x32_bf16 v[120:123], v[164:167], v[188:191], v[120:123]
	v_mfma_f32_16x16x32_bf16 v[108:111], v[156:159], v[196:199], v[108:111]
	v_mfma_f32_16x16x32_bf16 v[104:107], v[164:167], v[196:199], v[104:107]
	v_mfma_f32_16x16x32_bf16 v[92:95], v[156:159], v[204:207], v[92:95]
	v_mfma_f32_16x16x32_bf16 v[88:91], v[164:167], v[204:207], v[88:91]
	v_mfma_f32_16x16x32_bf16 v[76:79], v[156:159], v[212:215], v[76:79]
	v_mfma_f32_16x16x32_bf16 v[72:75], v[164:167], v[212:215], v[72:75]
	v_mfma_f32_16x16x32_bf16 v[116:119], v[168:171], v[184:187], v[116:119]
	v_mfma_f32_16x16x32_bf16 v[112:115], v[176:179], v[184:187], v[112:115]
	v_mfma_f32_16x16x32_bf16 v[100:103], v[168:171], v[192:195], v[100:103]
	v_mfma_f32_16x16x32_bf16 v[96:99], v[176:179], v[192:195], v[96:99]
	v_mfma_f32_16x16x32_bf16 v[84:87], v[168:171], v[200:203], v[84:87]
	v_mfma_f32_16x16x32_bf16 v[80:83], v[176:179], v[200:203], v[80:83]
	v_mfma_f32_16x16x32_bf16 v[68:71], v[168:171], v[208:211], v[68:71]
	v_mfma_f32_16x16x32_bf16 v[64:67], v[176:179], v[208:211], v[64:67]
	v_mfma_f32_16x16x32_bf16 v[116:119], v[172:175], v[188:191], v[116:119]
	v_mfma_f32_16x16x32_bf16 v[112:115], v[180:183], v[188:191], v[112:115]
	v_mfma_f32_16x16x32_bf16 v[100:103], v[172:175], v[196:199], v[100:103]
	v_mfma_f32_16x16x32_bf16 v[96:99], v[180:183], v[196:199], v[96:99]
	v_mfma_f32_16x16x32_bf16 v[84:87], v[172:175], v[204:207], v[84:87]
	v_mfma_f32_16x16x32_bf16 v[80:83], v[180:183], v[204:207], v[80:83]
	v_mfma_f32_16x16x32_bf16 v[68:71], v[172:175], v[212:215], v[68:71]
	v_mfma_f32_16x16x32_bf16 v[64:67], v[180:183], v[212:215], v[64:67]
	s_barrier
	s_setprio 0
	s_add_i32 s20, s40, s28
	v_lshl_add_u64 v[148:149], s[24:25], 0, v[130:131]
	s_mov_b32 m0, s20
	ds_read_b128 v[184:187], v155 offset:16384
	ds_read_b128 v[188:191], v155 offset:17408
	ds_read_b128 v[192:195], v155 offset:18432
	ds_read_b128 v[196:199], v155 offset:19456
	ds_read_b128 v[200:203], v155 offset:20480
	ds_read_b128 v[204:207], v155 offset:21504
	ds_read_b128 v[208:211], v155 offset:22528
	ds_read_b128 v[212:215], v155 offset:23552
	global_load_lds_dwordx4 v[148:149], off
	s_add_i32 m0, s20, 0x2000
	s_add_u32 s20, s24, 0x2b0000
	v_lshl_add_u64 v[216:217], s[24:25], 0, v[134:135]
	s_addc_u32 s21, s25, 0
	s_add_i32 s50, s41, s28
	global_load_lds_dwordx4 v[216:217], off
	v_lshl_add_u64 v[218:219], s[20:21], 0, v[130:131]
	s_mov_b32 m0, s50
	v_lshl_add_u64 v[220:221], s[26:27], 0, v[132:133]
	global_load_lds_dwordx4 v[218:219], off
	v_lshl_add_u64 v[218:219], s[20:21], 0, v[134:135]
	s_add_i32 m0, s50, 0x2000
	s_nop 0
	global_load_lds_dwordx4 v[218:219], off
	v_lshl_add_u64 v[218:219], s[26:27], 0, v[128:129]
	s_mov_b32 m0, s31
	s_nop 0
	global_load_lds_dwordx4 v[218:219], off
	s_mov_b32 m0, s33
	s_nop 0
	global_load_lds_dwordx4 v[220:221], off
	s_waitcnt vmcnt(8)
	s_waitcnt lgkmcnt(0)
	s_setprio 1
	s_barrier
; #define PG8_STAGE(bufoff, gbase, voff) do { _Pragma("unroll") for (int _i = 0; _i < 2; ++_i) \
;         __builtin_amdgcn_global_load_lds((const unsigned*)((const char*)(gbase) + (voff)[_i]), (LAS unsigned*)(lds + (bufoff) + ldsw + _i * 8192), 16, 0, 0); } while (0)
; #define PG8_LDA(dst, b, h) do { _Pragma("unroll") for (int m = 0; m < 4; ++m) _Pragma("unroll") for (int k = 0; k < 2; ++k) dst[m][k] = *(const LAS bf16x8*)(lds + PG8_SA(b, h) + aoff + m * 2048 + k * 1024); } while (0)
; #define PG8_LDB(dst, b, h) do { _Pragma("unroll") for (int n = 0; n < 2; ++n) _Pragma("unroll") for (int k = 0; k < 2; ++k) dst[n][k] = *(const LAS bf16x8*)(lds + PG8_SB(b, h) + boff + n * 2048 + k * 1024); } while (0)
; #define PG8_MMA(ai, bj, At, Bt) do { __builtin_amdgcn_s_setprio(1); _Pragma("unroll") for (int m = 0; m < 4; ++m) _Pragma("unroll") for (int n = 0; n < 2; ++n) _Pragma("unroll") for (int k = 0; k < 2; ++k) \
;         acc[ai][bj][m][n] = __builtin_amdgcn_mfma_f32_16x16x32_bf16(Bt[n][k], At[m][k], acc[ai][bj][m][n], 0, 0, 0); __builtin_amdgcn_s_setprio(0); } while (0)
; #define PG8_WAIT_V(n) asm volatile("s_waitcnt vmcnt(" #n ")" ::: "memory")
; #define PG8_WAIT_L(n) asm volatile("s_waitcnt lgkmcnt(" #n ")" ::: "memory")
; #define PG8_BAR __builtin_amdgcn_s_barrier()
; #define PG8_SCHED __builtin_amdgcn_sched_barrier(0)
; template <class Epi, bool ALIGN_EPI, bool SP2 = PG8_SP2_DEFAULT>
; __device__ __forceinline__ void gemm_phase(LAS unsigned char* lds, const Gemm g, const StaticOrder& S, const Epi& E) {
;     ...
;             PG8_WAIT_V(8); PG8_WAIT_L(0); PG8_BAR; PG8_MMA(1, 0, At, B0); PG8_MMA(1, 1, At, B1); PG8_BAR; PG8_SCHED;
;             PG8_LDB(B0, 1, 0); PG8_LDB(B1, 1, 1); PG8_SCHED; PG8_LDA(At, 1, 0); PG8_STAGE(PG8_SA(0, 1), a2 + hstepA, voffA);
;             PG8_WAIT_V(8); PG8_WAIT_L(0); PG8_BAR; PG8_MMA(0, 0, At, B0); PG8_MMA(0, 1, At, B1); PG8_BAR; PG8_SCHED;
	v_mfma_f32_16x16x32_bf16 v[60:63], v[144:147], v[184:187], v[60:63]
	v_mfma_f32_16x16x32_bf16 v[56:59], v[160:163], v[184:187], v[56:59]
	v_mfma_f32_16x16x32_bf16 v[44:47], v[144:147], v[192:195], v[44:47]
	v_mfma_f32_16x16x32_bf16 v[40:43], v[160:163], v[192:195], v[40:43]
	v_mfma_f32_16x16x32_bf16 v[28:31], v[144:147], v[200:203], v[28:31]
	v_mfma_f32_16x16x32_bf16 v[24:27], v[160:163], v[200:203], v[24:27]
	v_mfma_f32_16x16x32_bf16 v[12:15], v[144:147], v[208:211], v[12:15]
	v_mfma_f32_16x16x32_bf16 v[8:11], v[160:163], v[208:211], v[8:11]
	v_mfma_f32_16x16x32_bf16 v[60:63], v[156:159], v[188:191], v[60:63]
	v_mfma_f32_16x16x32_bf16 v[56:59], v[164:167], v[188:191], v[56:59]
	v_mfma_f32_16x16x32_bf16 v[44:47], v[156:159], v[196:199], v[44:47]
	v_mfma_f32_16x16x32_bf16 v[40:43], v[164:167], v[196:199], v[40:43]
	v_mfma_f32_16x16x32_bf16 v[28:31], v[156:159], v[204:207], v[28:31]
	v_mfma_f32_16x16x32_bf16 v[24:27], v[164:167], v[204:207], v[24:27]
	v_mfma_f32_16x16x32_bf16 v[12:15], v[156:159], v[212:215], v[12:15]
	v_mfma_f32_16x16x32_bf16 v[8:11], v[164:167], v[212:215], v[8:11]
	v_mfma_f32_16x16x32_bf16 v[52:55], v[168:171], v[184:187], v[52:55]
	v_mfma_f32_16x16x32_bf16 v[48:51], v[176:179], v[184:187], v[48:51]
	v_mfma_f32_16x16x32_bf16 v[36:39], v[168:171], v[192:195], v[36:39]
	v_mfma_f32_16x16x32_bf16 v[32:35], v[176:179], v[192:195], v[32:35]
	v_mfma_f32_16x16x32_bf16 v[20:23], v[168:171], v[200:203], v[20:23]
	v_mfma_f32_16x16x32_bf16 v[16:19], v[176:179], v[200:203], v[16:19]
	v_mfma_f32_16x16x32_bf16 v[4:7], v[168:171], v[208:211], v[4:7]
	v_mfma_f32_16x16x32_bf16 v[0:3], v[176:179], v[208:211], v[0:3]
	v_mfma_f32_16x16x32_bf16 v[52:55], v[172:175], v[188:191], v[52:55]
	v_mfma_f32_16x16x32_bf16 v[48:51], v[180:183], v[188:191], v[48:51]
	v_mfma_f32_16x16x32_bf16 v[36:39], v[172:175], v[196:199], v[36:39]
	v_mfma_f32_16x16x32_bf16 v[32:35], v[180:183], v[196:199], v[32:35]
	v_mfma_f32_16x16x32_bf16 v[20:23], v[172:175], v[204:207], v[20:23]
	v_mfma_f32_16x16x32_bf16 v[16:19], v[180:183], v[204:207], v[16:19]
	v_mfma_f32_16x16x32_bf16 v[4:7], v[172:175], v[212:215], v[4:7]
	v_mfma_f32_16x16x32_bf16 v[0:3], v[180:183], v[212:215], v[0:3]
	s_barrier
	s_setprio 0
	s_add_i32 s50, 0, 0x18000
	s_add_i32 s51, 0, 0x1c000
	v_add_u32_e32 v164, s50, v151
	v_add_u32_e32 v180, s51, v151
	ds_read_b128 v[144:147], v164
	ds_read_b128 v[156:159], v164 offset:1024
	ds_read_b128 v[160:163], v164 offset:2048
	ds_read_b128 v[164:167], v164 offset:3072
	ds_read_b128 v[168:171], v180
	ds_read_b128 v[172:175], v180 offset:1024
	ds_read_b128 v[176:179], v180 offset:2048
	ds_read_b128 v[180:183], v180 offset:3072
	s_add_u32 s20, s26, 0x2b0000
	s_addc_u32 s21, s27, 0
	s_mov_b32 m0, s34
	v_lshl_add_u64 v[222:223], s[20:21], 0, v[128:129]
	ds_read_b128 v[184:187], v155 offset:32768
	ds_read_b128 v[188:191], v155 offset:33792
	ds_read_b128 v[192:195], v155 offset:34816
	ds_read_b128 v[196:199], v155 offset:35840
	ds_read_b128 v[200:203], v155 offset:36864
	ds_read_b128 v[204:207], v155 offset:37888
	ds_read_b128 v[208:211], v155 offset:38912
	ds_read_b128 v[212:215], v155 offset:39936
	global_load_lds_dwordx4 v[222:223], off
	v_lshl_add_u64 v[222:223], s[20:21], 0, v[132:133]
	s_mov_b32 m0, s35
	s_nop 0
	global_load_lds_dwordx4 v[222:223], off
	s_waitcnt vmcnt(8)
	s_waitcnt lgkmcnt(0)
	s_setprio 1
	s_barrier
	v_mfma_f32_16x16x32_bf16 v[124:127], v[144:147], v[184:187], v[124:127]
	v_mfma_f32_16x16x32_bf16 v[120:123], v[160:163], v[184:187], v[120:123]
	v_mfma_f32_16x16x32_bf16 v[108:111], v[144:147], v[192:195], v[108:111]
	v_mfma_f32_16x16x32_bf16 v[104:107], v[160:163], v[192:195], v[104:107]
	v_mfma_f32_16x16x32_bf16 v[92:95], v[144:147], v[200:203], v[92:95]
	v_mfma_f32_16x16x32_bf16 v[88:91], v[160:163], v[200:203], v[88:91]
	v_mfma_f32_16x16x32_bf16 v[76:79], v[144:147], v[208:211], v[76:79]
	v_mfma_f32_16x16x32_bf16 v[72:75], v[160:163], v[208:211], v[72:75]
	v_mfma_f32_16x16x32_bf16 v[124:127], v[156:159], v[188:191], v[124:127]
	v_mfma_f32_16x16x32_bf16 v[120:123], v[164:167], v[188:191], v[120:123]
	v_mfma_f32_16x16x32_bf16 v[108:111], v[156:159], v[196:199], v[108:111]
	v_mfma_f32_16x16x32_bf16 v[104:107], v[164:167], v[196:199], v[104:107]
	v_mfma_f32_16x16x32_bf16 v[92:95], v[156:159], v[204:207], v[92:95]
	v_mfma_f32_16x16x32_bf16 v[88:91], v[164:167], v[204:207], v[88:91]
	v_mfma_f32_16x16x32_bf16 v[76:79], v[156:159], v[212:215], v[76:79]
	v_mfma_f32_16x16x32_bf16 v[72:75], v[164:167], v[212:215], v[72:75]
	v_mfma_f32_16x16x32_bf16 v[116:119], v[168:171], v[184:187], v[116:119]
	v_mfma_f32_16x16x32_bf16 v[112:115], v[176:179], v[184:187], v[112:115]
	v_mfma_f32_16x16x32_bf16 v[100:103], v[168:171], v[192:195], v[100:103]
	v_mfma_f32_16x16x32_bf16 v[96:99], v[176:179], v[192:195], v[96:99]
	v_mfma_f32_16x16x32_bf16 v[84:87], v[168:171], v[200:203], v[84:87]
	v_mfma_f32_16x16x32_bf16 v[80:83], v[176:179], v[200:203], v[80:83]
	v_mfma_f32_16x16x32_bf16 v[68:71], v[168:171], v[208:211], v[68:71]
	v_mfma_f32_16x16x32_bf16 v[64:67], v[176:179], v[208:211], v[64:67]
	v_mfma_f32_16x16x32_bf16 v[116:119], v[172:175], v[188:191], v[116:119]
	v_mfma_f32_16x16x32_bf16 v[112:115], v[180:183], v[188:191], v[112:115]
	v_mfma_f32_16x16x32_bf16 v[100:103], v[172:175], v[196:199], v[100:103]
	v_mfma_f32_16x16x32_bf16 v[96:99], v[180:183], v[196:199], v[96:99]
	v_mfma_f32_16x16x32_bf16 v[84:87], v[172:175], v[204:207], v[84:87]
	v_mfma_f32_16x16x32_bf16 v[80:83], v[180:183], v[204:207], v[80:83]
	v_mfma_f32_16x16x32_bf16 v[68:71], v[172:175], v[212:215], v[68:71]
	v_mfma_f32_16x16x32_bf16 v[64:67], v[180:183], v[212:215], v[64:67]
	s_barrier
; #define PG8_STAGE(bufoff, gbase, voff) do { _Pragma("unroll") for (int _i = 0; _i < 2; ++_i) \
;         __builtin_amdgcn_global_load_lds((const unsigned*)((const char*)(gbase) + (voff)[_i]), (LAS unsigned*)(lds + (bufoff) + ldsw + _i * 8192), 16, 0, 0); } while (0)
; #define PG8_LDA(dst, b, h) do { _Pragma("unroll") for (int m = 0; m < 4; ++m) _Pragma("unroll") for (int k = 0; k < 2; ++k) dst[m][k] = *(const LAS bf16x8*)(lds + PG8_SA(b, h) + aoff + m * 2048 + k * 1024); } while (0)
; #define PG8_MMA(ai, bj, At, Bt) do { __builtin_amdgcn_s_setprio(1); _Pragma("unroll") for (int m = 0; m < 4; ++m) _Pragma("unroll") for (int n = 0; n < 2; ++n) _Pragma("unroll") for (int k = 0; k < 2; ++k) \
;         acc[ai][bj][m][n] = __builtin_amdgcn_mfma_f32_16x16x32_bf16(Bt[n][k], At[m][k], acc[ai][bj][m][n], 0, 0, 0); __builtin_amdgcn_s_setprio(0); } while (0)
; #define PG8_WAIT_V(n) asm volatile("s_waitcnt vmcnt(" #n ")" ::: "memory")
; #define PG8_WAIT_L(n) asm volatile("s_waitcnt lgkmcnt(" #n ")" ::: "memory")
; #define PG8_BAR __builtin_amdgcn_s_barrier()
; #define PG8_SCHED __builtin_amdgcn_sched_barrier(0)
; template <class Epi, bool ALIGN_EPI, bool SP2 = PG8_SP2_DEFAULT>
; __device__ __forceinline__ void gemm_phase(LAS unsigned char* lds, const Gemm g, const StaticOrder& S, const Epi& E) {
;     ...
;         for (int t = 0; t < nt; t += 2) {
;     ...
;             PG8_LDA(At, 1, 1); PG8_STAGE(PG8_SB(1, 0), b3, voffB); PG8_STAGE(PG8_SB(1, 1), b3 + hstepB, voffB); PG8_STAGE(PG8_SA(1, 0), a3, voffA);
;             PG8_WAIT_V(8); PG8_WAIT_L(0); PG8_BAR; PG8_MMA(1, 0, At, B0); PG8_MMA(1, 1, At, B1); PG8_BAR; PG8_SCHED;
	s_setprio 0
	s_add_i32 s20, s50, s28
	v_lshl_add_u64 v[148:149], v[148:149], 0, s[6:7]
	s_mov_b32 m0, s20
	ds_read_b128 v[184:187], v155 offset:49152
	ds_read_b128 v[188:191], v155 offset:50176
	ds_read_b128 v[192:195], v155 offset:51200
	ds_read_b128 v[196:199], v155 offset:52224
	ds_read_b128 v[200:203], v155 offset:53248
	ds_read_b128 v[204:207], v155 offset:54272
	ds_read_b128 v[208:211], v155 offset:55296
	ds_read_b128 v[212:215], v155 offset:56320
	global_load_lds_dwordx4 v[148:149], off
	s_add_i32 m0, s20, 0x2000
	s_add_u32 s20, s24, 0x2b0080
	v_lshl_add_u64 v[148:149], v[216:217], 0, s[6:7]
	s_addc_u32 s21, s25, 0
	s_add_i32 s24, s51, s28
	global_load_lds_dwordx4 v[148:149], off
	v_lshl_add_u64 v[148:149], s[20:21], 0, v[130:131]
	s_mov_b32 m0, s24
	s_nop 0
	global_load_lds_dwordx4 v[148:149], off
	v_lshl_add_u64 v[148:149], s[20:21], 0, v[134:135]
	s_add_i32 m0, s24, 0x2000
	s_nop 0
	global_load_lds_dwordx4 v[148:149], off
	v_lshl_add_u64 v[148:149], v[218:219], 0, s[6:7]
	s_mov_b32 m0, s37
	s_nop 0
	global_load_lds_dwordx4 v[148:149], off
	v_lshl_add_u64 v[148:149], v[220:221], 0, s[6:7]
	s_mov_b32 m0, s38
	s_nop 0
	global_load_lds_dwordx4 v[148:149], off
	s_waitcnt vmcnt(8)
	s_waitcnt lgkmcnt(0)
	s_setprio 1
	s_barrier
	v_mfma_f32_16x16x32_bf16 v[60:63], v[144:147], v[184:187], v[60:63]
	v_mfma_f32_16x16x32_bf16 v[56:59], v[160:163], v[184:187], v[56:59]
	v_mfma_f32_16x16x32_bf16 v[44:47], v[144:147], v[192:195], v[44:47]
	v_mfma_f32_16x16x32_bf16 v[40:43], v[160:163], v[192:195], v[40:43]
	v_mfma_f32_16x16x32_bf16 v[28:31], v[144:147], v[200:203], v[28:31]
	v_mfma_f32_16x16x32_bf16 v[24:27], v[160:163], v[200:203], v[24:27]
	v_mfma_f32_16x16x32_bf16 v[12:15], v[144:147], v[208:211], v[12:15]
	v_mfma_f32_16x16x32_bf16 v[8:11], v[160:163], v[208:211], v[8:11]
	v_mfma_f32_16x16x32_bf16 v[60:63], v[156:159], v[188:191], v[60:63]
	v_mfma_f32_16x16x32_bf16 v[56:59], v[164:167], v[188:191], v[56:59]
	v_mfma_f32_16x16x32_bf16 v[44:47], v[156:159], v[196:199], v[44:47]
	v_mfma_f32_16x16x32_bf16 v[40:43], v[164:167], v[196:199], v[40:43]
	v_mfma_f32_16x16x32_bf16 v[28:31], v[156:159], v[204:207], v[28:31]
	v_mfma_f32_16x16x32_bf16 v[24:27], v[164:167], v[204:207], v[24:27]
	v_mfma_f32_16x16x32_bf16 v[12:15], v[156:159], v[212:215], v[12:15]
	v_mfma_f32_16x16x32_bf16 v[8:11], v[164:167], v[212:215], v[8:11]
	v_mfma_f32_16x16x32_bf16 v[52:55], v[168:171], v[184:187], v[52:55]
	v_mfma_f32_16x16x32_bf16 v[48:51], v[176:179], v[184:187], v[48:51]
	v_mfma_f32_16x16x32_bf16 v[36:39], v[168:171], v[192:195], v[36:39]
	v_mfma_f32_16x16x32_bf16 v[32:35], v[176:179], v[192:195], v[32:35]
	v_mfma_f32_16x16x32_bf16 v[20:23], v[168:171], v[200:203], v[20:23]
	v_mfma_f32_16x16x32_bf16 v[16:19], v[176:179], v[200:203], v[16:19]
	v_mfma_f32_16x16x32_bf16 v[4:7], v[168:171], v[208:211], v[4:7]
	v_mfma_f32_16x16x32_bf16 v[0:3], v[176:179], v[208:211], v[0:3]
	v_mfma_f32_16x16x32_bf16 v[52:55], v[172:175], v[188:191], v[52:55]
	v_mfma_f32_16x16x32_bf16 v[48:51], v[180:183], v[188:191], v[48:51]
	v_mfma_f32_16x16x32_bf16 v[36:39], v[172:175], v[196:199], v[36:39]
	v_mfma_f32_16x16x32_bf16 v[32:35], v[180:183], v[196:199], v[32:35]
	v_mfma_f32_16x16x32_bf16 v[20:23], v[172:175], v[204:207], v[20:23]
	v_mfma_f32_16x16x32_bf16 v[16:19], v[180:183], v[204:207], v[16:19]
	v_mfma_f32_16x16x32_bf16 v[4:7], v[172:175], v[212:215], v[4:7]
	v_mfma_f32_16x16x32_bf16 v[0:3], v[180:183], v[212:215], v[0:3]
	s_barrier
	s_setprio 0
	s_add_i32 s49, s49, 2
	s_add_u32 s47, s47, 0x100
	s_addc_u32 s48, s48, 0
	s_cmpk_gt_u32 s49, 0xa9
	s_mov_b64 s[20:21], s[22:23]
	s_cbranch_scc0 .LBB0_804
	s_and_b64 vcc, exec, s[8:9]
	s_cbranch_vccz .LBB0_807
	s_barrier
